# wt3_pz with the first-wait skip tests only in the peeled first iteration (main K-loops wait unconditionally)
# speedup vs baseline: 1.0174x; 1.0154x over previous
.LBB0_322:
	s_add_u32 s4, s0, 0xfffc0080
	s_addc_u32 s5, s1, -1
	s_add_i32 s44, 0, 0x10000
	s_cmp_eq_u32 s93, 12
	s_cselect_b32 s71, s31, s5
	s_cselect_b32 s70, s39, s4
	s_cselect_b32 s69, s41, s92
	s_cselect_b32 s68, s40, s91
	s_add_i32 s4, 0, 0x14000
	v_add_u32_e32 v144, s44, v175
	v_add_u32_e32 v168, s4, v175
	ds_read_b128 v[132:135], v144
	ds_read_b128 v[136:139], v144 offset:1024
	ds_read_b128 v[140:143], v144 offset:2048
	ds_read_b128 v[144:147], v144 offset:3072
	ds_read_b128 v[156:159], v168
	ds_read_b128 v[160:163], v168 offset:1024
	ds_read_b128 v[164:167], v168 offset:2048
	ds_read_b128 v[180:183], v168 offset:3072
	s_add_i32 s94, s77, 0
	v_lshl_add_u64 v[168:169], s[0:1], 0, v[98:99]
	s_add_i32 m0, s94, 0xc000
	ds_read_b128 v[184:187], v179
	ds_read_b128 v[188:191], v179 offset:1024
	ds_read_b128 v[192:195], v179 offset:2048
	ds_read_b128 v[204:207], v179 offset:3072
	ds_read_b128 v[208:211], v179 offset:4096
	ds_read_b128 v[212:215], v179 offset:5120
	ds_read_b128 v[216:219], v179 offset:6144
	ds_read_b128 v[220:223], v179 offset:7168
	global_load_lds_dwordx4 v[168:169], off
	v_lshl_add_u64 v[168:169], s[0:1], 0, v[150:151]
	s_add_i32 m0, s94, 0xe000
	s_nop 0
	global_load_lds_dwordx4 v[168:169], off
	s_waitcnt vmcnt(8)
	s_waitcnt lgkmcnt(0)
	s_setprio 1
	s_barrier
	v_mfma_f32_16x16x32_bf16 v[128:131], v[132:135], v[184:187], v[128:131]
	v_mfma_f32_16x16x32_bf16 v[124:127], v[140:143], v[184:187], v[124:127]
	v_mfma_f32_16x16x32_bf16 v[120:123], v[132:135], v[192:195], v[120:123]
	v_mfma_f32_16x16x32_bf16 v[112:115], v[140:143], v[192:195], v[112:115]
	v_mfma_f32_16x16x32_bf16 v[104:107], v[132:135], v[208:211], v[104:107]
	v_mfma_f32_16x16x32_bf16 v[94:97], v[140:143], v[208:211], v[94:97]
	v_mfma_f32_16x16x32_bf16 v[86:89], v[132:135], v[216:219], v[86:89]
	v_mfma_f32_16x16x32_bf16 v[78:81], v[140:143], v[216:219], v[78:81]
	v_mfma_f32_16x16x32_bf16 v[128:131], v[136:139], v[188:191], v[128:131]
	v_mfma_f32_16x16x32_bf16 v[124:127], v[144:147], v[188:191], v[124:127]
	v_mfma_f32_16x16x32_bf16 v[120:123], v[136:139], v[204:207], v[120:123]
	v_mfma_f32_16x16x32_bf16 v[112:115], v[144:147], v[204:207], v[112:115]
	v_mfma_f32_16x16x32_bf16 v[104:107], v[136:139], v[212:215], v[104:107]
	v_mfma_f32_16x16x32_bf16 v[94:97], v[144:147], v[212:215], v[94:97]
	v_mfma_f32_16x16x32_bf16 v[86:89], v[136:139], v[220:223], v[86:89]
	v_mfma_f32_16x16x32_bf16 v[78:81], v[144:147], v[220:223], v[78:81]
	s_setprio 0
	s_setprio 1
	v_mfma_f32_16x16x32_bf16 v[116:119], v[156:159], v[184:187], v[116:119]
	v_mfma_f32_16x16x32_bf16 v[108:111], v[164:167], v[184:187], v[108:111]
	v_mfma_f32_16x16x32_bf16 v[100:103], v[156:159], v[192:195], v[100:103]
	v_mfma_f32_16x16x32_bf16 v[90:93], v[164:167], v[192:195], v[90:93]
	v_mfma_f32_16x16x32_bf16 v[82:85], v[156:159], v[208:211], v[82:85]
	v_mfma_f32_16x16x32_bf16 v[74:77], v[164:167], v[208:211], v[74:77]
	v_mfma_f32_16x16x32_bf16 v[70:73], v[156:159], v[216:219], v[70:73]
	v_mfma_f32_16x16x32_bf16 v[66:69], v[164:167], v[216:219], v[66:69]
	v_mfma_f32_16x16x32_bf16 v[116:119], v[160:163], v[188:191], v[116:119]
	v_mfma_f32_16x16x32_bf16 v[108:111], v[180:183], v[188:191], v[108:111]
	v_mfma_f32_16x16x32_bf16 v[100:103], v[160:163], v[204:207], v[100:103]
	v_mfma_f32_16x16x32_bf16 v[90:93], v[180:183], v[204:207], v[90:93]
	v_mfma_f32_16x16x32_bf16 v[82:85], v[160:163], v[212:215], v[82:85]
	v_mfma_f32_16x16x32_bf16 v[74:77], v[180:183], v[212:215], v[74:77]
	v_mfma_f32_16x16x32_bf16 v[70:73], v[160:163], v[220:223], v[70:73]
	v_mfma_f32_16x16x32_bf16 v[66:69], v[180:183], v[220:223], v[66:69]
	s_setprio 0
	s_barrier
	s_add_i32 s5, s44, s77
	v_lshl_add_u64 v[168:169], s[68:69], 0, v[148:149]
	s_mov_b32 m0, s5
	ds_read_b128 v[184:187], v179 offset:16384
	ds_read_b128 v[188:191], v179 offset:17408
	ds_read_b128 v[192:195], v179 offset:18432
	ds_read_b128 v[204:207], v179 offset:19456
	ds_read_b128 v[208:211], v179 offset:20480
	ds_read_b128 v[212:215], v179 offset:21504
	ds_read_b128 v[216:219], v179 offset:22528
	ds_read_b128 v[220:223], v179 offset:23552
	global_load_lds_dwordx4 v[168:169], off
	s_add_i32 m0, s5, 0x2000
	s_add_u32 s44, s68, 0x40000
	v_lshl_add_u64 v[172:173], s[68:69], 0, v[152:153]
	s_addc_u32 s45, s69, 0
	s_add_i32 s4, s4, s77
	global_load_lds_dwordx4 v[172:173], off
	v_lshl_add_u64 v[176:177], s[44:45], 0, v[148:149]
	s_mov_b32 m0, s4
	v_lshl_add_u64 v[200:201], s[70:71], 0, v[150:151]
	global_load_lds_dwordx4 v[176:177], off
	v_lshl_add_u64 v[176:177], s[44:45], 0, v[152:153]
	s_add_i32 m0, s4, 0x2000
	s_nop 0
	global_load_lds_dwordx4 v[176:177], off
	v_lshl_add_u64 v[176:177], s[70:71], 0, v[98:99]
	s_mov_b32 m0, s94
	s_nop 0
	global_load_lds_dwordx4 v[176:177], off
	s_add_i32 m0, s94, 0x2000
	s_nop 0
	global_load_lds_dwordx4 v[200:201], off
	s_waitcnt vmcnt(8)
	s_waitcnt lgkmcnt(0)
	s_setprio 1
	s_barrier
	v_mfma_f32_16x16x32_bf16 v[62:65], v[132:135], v[184:187], v[62:65]
	v_mfma_f32_16x16x32_bf16 v[58:61], v[140:143], v[184:187], v[58:61]
	v_mfma_f32_16x16x32_bf16 v[54:57], v[132:135], v[192:195], v[54:57]
	v_mfma_f32_16x16x32_bf16 v[46:49], v[140:143], v[192:195], v[46:49]
	v_mfma_f32_16x16x32_bf16 v[38:41], v[132:135], v[208:211], v[38:41]
	v_mfma_f32_16x16x32_bf16 v[30:33], v[140:143], v[208:211], v[30:33]
	v_mfma_f32_16x16x32_bf16 v[22:25], v[132:135], v[216:219], v[22:25]
	v_mfma_f32_16x16x32_bf16 v[14:17], v[140:143], v[216:219], v[14:17]
	v_mfma_f32_16x16x32_bf16 v[62:65], v[136:139], v[188:191], v[62:65]
	v_mfma_f32_16x16x32_bf16 v[58:61], v[144:147], v[188:191], v[58:61]
	v_mfma_f32_16x16x32_bf16 v[54:57], v[136:139], v[204:207], v[54:57]
	v_mfma_f32_16x16x32_bf16 v[46:49], v[144:147], v[204:207], v[46:49]
	v_mfma_f32_16x16x32_bf16 v[38:41], v[136:139], v[212:215], v[38:41]
	v_mfma_f32_16x16x32_bf16 v[30:33], v[144:147], v[212:215], v[30:33]
	v_mfma_f32_16x16x32_bf16 v[22:25], v[136:139], v[220:223], v[22:25]
	v_mfma_f32_16x16x32_bf16 v[14:17], v[144:147], v[220:223], v[14:17]
	s_setprio 0
	s_setprio 1
	v_mfma_f32_16x16x32_bf16 v[50:53], v[156:159], v[184:187], v[50:53]
	v_mfma_f32_16x16x32_bf16 v[42:45], v[164:167], v[184:187], v[42:45]
	v_mfma_f32_16x16x32_bf16 v[34:37], v[156:159], v[192:195], v[34:37]
	v_mfma_f32_16x16x32_bf16 v[26:29], v[164:167], v[192:195], v[26:29]
	v_mfma_f32_16x16x32_bf16 v[18:21], v[156:159], v[208:211], v[18:21]
	v_mfma_f32_16x16x32_bf16 v[10:13], v[164:167], v[208:211], v[10:13]
	v_mfma_f32_16x16x32_bf16 v[6:9], v[156:159], v[216:219], v[6:9]
	v_mfma_f32_16x16x32_bf16 v[2:5], v[164:167], v[216:219], v[2:5]
	v_mfma_f32_16x16x32_bf16 v[50:53], v[160:163], v[188:191], v[50:53]
	v_mfma_f32_16x16x32_bf16 v[42:45], v[180:183], v[188:191], v[42:45]
	v_mfma_f32_16x16x32_bf16 v[34:37], v[160:163], v[204:207], v[34:37]
	v_mfma_f32_16x16x32_bf16 v[26:29], v[180:183], v[204:207], v[26:29]
	v_mfma_f32_16x16x32_bf16 v[18:21], v[160:163], v[212:215], v[18:21]
	v_mfma_f32_16x16x32_bf16 v[10:13], v[180:183], v[212:215], v[10:13]
	v_mfma_f32_16x16x32_bf16 v[6:9], v[160:163], v[220:223], v[6:9]
	v_mfma_f32_16x16x32_bf16 v[2:5], v[180:183], v[220:223], v[2:5]
	s_setprio 0
	s_barrier
	s_add_i32 s4, 0, 0x18000
	s_add_i32 s5, 0, 0x1c000
	v_add_u32_e32 v144, s4, v175
	v_add_u32_e32 v170, s5, v175
	ds_read_b128 v[132:135], v144
	ds_read_b128 v[136:139], v144 offset:1024
	ds_read_b128 v[140:143], v144 offset:2048
	ds_read_b128 v[144:147], v144 offset:3072
	ds_read_b128 v[156:159], v170
	ds_read_b128 v[160:163], v170 offset:1024
	ds_read_b128 v[164:167], v170 offset:2048
	ds_read_b128 v[180:183], v170 offset:3072
	s_add_u32 s44, s70, 0x40000
	s_addc_u32 s45, s71, 0
	v_lshl_add_u64 v[202:203], s[44:45], 0, v[98:99]
	s_add_i32 m0, s94, 0x4000
	ds_read_b128 v[184:187], v179 offset:32768
	ds_read_b128 v[188:191], v179 offset:33792
	ds_read_b128 v[192:195], v179 offset:34816
	ds_read_b128 v[204:207], v179 offset:35840
	ds_read_b128 v[208:211], v179 offset:36864
	ds_read_b128 v[212:215], v179 offset:37888
	ds_read_b128 v[216:219], v179 offset:38912
	ds_read_b128 v[220:223], v179 offset:39936
	global_load_lds_dwordx4 v[202:203], off
	v_lshl_add_u64 v[202:203], s[44:45], 0, v[150:151]
	s_add_i32 m0, s94, 0x6000
	s_nop 0
	global_load_lds_dwordx4 v[202:203], off
	s_waitcnt vmcnt(8)
	s_waitcnt lgkmcnt(0)
	s_setprio 1
	s_barrier
	v_mfma_f32_16x16x32_bf16 v[128:131], v[132:135], v[184:187], v[128:131]
	v_mfma_f32_16x16x32_bf16 v[124:127], v[140:143], v[184:187], v[124:127]
	v_mfma_f32_16x16x32_bf16 v[120:123], v[132:135], v[192:195], v[120:123]
	v_mfma_f32_16x16x32_bf16 v[112:115], v[140:143], v[192:195], v[112:115]
	v_mfma_f32_16x16x32_bf16 v[104:107], v[132:135], v[208:211], v[104:107]
	v_mfma_f32_16x16x32_bf16 v[94:97], v[140:143], v[208:211], v[94:97]
	v_mfma_f32_16x16x32_bf16 v[86:89], v[132:135], v[216:219], v[86:89]
	v_mfma_f32_16x16x32_bf16 v[78:81], v[140:143], v[216:219], v[78:81]
	v_mfma_f32_16x16x32_bf16 v[128:131], v[136:139], v[188:191], v[128:131]
	v_mfma_f32_16x16x32_bf16 v[124:127], v[144:147], v[188:191], v[124:127]
	v_mfma_f32_16x16x32_bf16 v[120:123], v[136:139], v[204:207], v[120:123]
	v_mfma_f32_16x16x32_bf16 v[112:115], v[144:147], v[204:207], v[112:115]
	v_mfma_f32_16x16x32_bf16 v[104:107], v[136:139], v[212:215], v[104:107]
	v_mfma_f32_16x16x32_bf16 v[94:97], v[144:147], v[212:215], v[94:97]
	v_mfma_f32_16x16x32_bf16 v[86:89], v[136:139], v[220:223], v[86:89]
	v_mfma_f32_16x16x32_bf16 v[78:81], v[144:147], v[220:223], v[78:81]
	s_setprio 0
	s_setprio 1
	v_mfma_f32_16x16x32_bf16 v[116:119], v[156:159], v[184:187], v[116:119]
	v_mfma_f32_16x16x32_bf16 v[108:111], v[164:167], v[184:187], v[108:111]
	v_mfma_f32_16x16x32_bf16 v[100:103], v[156:159], v[192:195], v[100:103]
	v_mfma_f32_16x16x32_bf16 v[90:93], v[164:167], v[192:195], v[90:93]
	v_mfma_f32_16x16x32_bf16 v[82:85], v[156:159], v[208:211], v[82:85]
	v_mfma_f32_16x16x32_bf16 v[74:77], v[164:167], v[208:211], v[74:77]
	v_mfma_f32_16x16x32_bf16 v[70:73], v[156:159], v[216:219], v[70:73]
	v_mfma_f32_16x16x32_bf16 v[66:69], v[164:167], v[216:219], v[66:69]
	v_mfma_f32_16x16x32_bf16 v[116:119], v[160:163], v[188:191], v[116:119]
	v_mfma_f32_16x16x32_bf16 v[108:111], v[180:183], v[188:191], v[108:111]
	v_mfma_f32_16x16x32_bf16 v[100:103], v[160:163], v[204:207], v[100:103]
	v_mfma_f32_16x16x32_bf16 v[90:93], v[180:183], v[204:207], v[90:93]
	v_mfma_f32_16x16x32_bf16 v[82:85], v[160:163], v[212:215], v[82:85]
	v_mfma_f32_16x16x32_bf16 v[74:77], v[180:183], v[212:215], v[74:77]
	v_mfma_f32_16x16x32_bf16 v[70:73], v[160:163], v[220:223], v[70:73]
	v_mfma_f32_16x16x32_bf16 v[66:69], v[180:183], v[220:223], v[66:69]
	s_setprio 0
	s_barrier
	s_add_i32 s4, s4, s77
	v_lshl_add_u64 v[168:169], v[168:169], 0, s[42:43]
	s_mov_b32 m0, s4
	ds_read_b128 v[184:187], v179 offset:49152
	ds_read_b128 v[188:191], v179 offset:50176
	ds_read_b128 v[192:195], v179 offset:51200
	ds_read_b128 v[204:207], v179 offset:52224
	ds_read_b128 v[208:211], v179 offset:53248
	ds_read_b128 v[212:215], v179 offset:54272
	ds_read_b128 v[216:219], v179 offset:55296
	ds_read_b128 v[220:223], v179 offset:56320
	global_load_lds_dwordx4 v[168:169], off
	s_add_i32 m0, s4, 0x2000
	s_add_u32 s44, s68, 0x40080
	v_lshl_add_u64 v[168:169], v[172:173], 0, s[42:43]
	s_addc_u32 s45, s69, 0
	s_add_i32 s4, s5, s77
	global_load_lds_dwordx4 v[168:169], off
	v_lshl_add_u64 v[168:169], s[44:45], 0, v[148:149]
	s_mov_b32 m0, s4
	s_nop 0
	global_load_lds_dwordx4 v[168:169], off
	v_lshl_add_u64 v[168:169], s[44:45], 0, v[152:153]
	s_add_i32 m0, s4, 0x2000
	s_nop 0
	global_load_lds_dwordx4 v[168:169], off
	v_lshl_add_u64 v[168:169], v[176:177], 0, s[42:43]
	s_add_i32 m0, s94, 0x8000
	s_nop 0
	global_load_lds_dwordx4 v[168:169], off
	v_lshl_add_u64 v[168:169], v[200:201], 0, s[42:43]
	s_add_i32 m0, s94, 0xa000
	s_nop 0
	global_load_lds_dwordx4 v[168:169], off
	s_waitcnt vmcnt(8)
	s_waitcnt lgkmcnt(0)
	s_setprio 1
	s_barrier
	v_mfma_f32_16x16x32_bf16 v[62:65], v[132:135], v[184:187], v[62:65]
	v_mfma_f32_16x16x32_bf16 v[58:61], v[140:143], v[184:187], v[58:61]
	v_mfma_f32_16x16x32_bf16 v[54:57], v[132:135], v[192:195], v[54:57]
	v_mfma_f32_16x16x32_bf16 v[46:49], v[140:143], v[192:195], v[46:49]
	v_mfma_f32_16x16x32_bf16 v[38:41], v[132:135], v[208:211], v[38:41]
	v_mfma_f32_16x16x32_bf16 v[30:33], v[140:143], v[208:211], v[30:33]
	v_mfma_f32_16x16x32_bf16 v[22:25], v[132:135], v[216:219], v[22:25]
	v_mfma_f32_16x16x32_bf16 v[14:17], v[140:143], v[216:219], v[14:17]
	v_mfma_f32_16x16x32_bf16 v[62:65], v[136:139], v[188:191], v[62:65]
	v_mfma_f32_16x16x32_bf16 v[58:61], v[144:147], v[188:191], v[58:61]
	v_mfma_f32_16x16x32_bf16 v[54:57], v[136:139], v[204:207], v[54:57]
	v_mfma_f32_16x16x32_bf16 v[46:49], v[144:147], v[204:207], v[46:49]
	v_mfma_f32_16x16x32_bf16 v[38:41], v[136:139], v[212:215], v[38:41]
	v_mfma_f32_16x16x32_bf16 v[30:33], v[144:147], v[212:215], v[30:33]
	v_mfma_f32_16x16x32_bf16 v[22:25], v[136:139], v[220:223], v[22:25]
	v_mfma_f32_16x16x32_bf16 v[14:17], v[144:147], v[220:223], v[14:17]
	s_setprio 0
	s_setprio 1
	v_mfma_f32_16x16x32_bf16 v[50:53], v[156:159], v[184:187], v[50:53]
	v_mfma_f32_16x16x32_bf16 v[42:45], v[164:167], v[184:187], v[42:45]
	v_mfma_f32_16x16x32_bf16 v[34:37], v[156:159], v[192:195], v[34:37]
	v_mfma_f32_16x16x32_bf16 v[26:29], v[164:167], v[192:195], v[26:29]
	v_mfma_f32_16x16x32_bf16 v[18:21], v[156:159], v[208:211], v[18:21]
	v_mfma_f32_16x16x32_bf16 v[10:13], v[164:167], v[208:211], v[10:13]
	v_mfma_f32_16x16x32_bf16 v[6:9], v[156:159], v[216:219], v[6:9]
	v_mfma_f32_16x16x32_bf16 v[2:5], v[164:167], v[216:219], v[2:5]
	v_mfma_f32_16x16x32_bf16 v[50:53], v[160:163], v[188:191], v[50:53]
	v_mfma_f32_16x16x32_bf16 v[42:45], v[180:183], v[188:191], v[42:45]
	v_mfma_f32_16x16x32_bf16 v[34:37], v[160:163], v[204:207], v[34:37]
	v_mfma_f32_16x16x32_bf16 v[26:29], v[180:183], v[204:207], v[26:29]
	v_mfma_f32_16x16x32_bf16 v[18:21], v[160:163], v[212:215], v[18:21]
	v_mfma_f32_16x16x32_bf16 v[10:13], v[180:183], v[212:215], v[10:13]
	v_mfma_f32_16x16x32_bf16 v[6:9], v[160:163], v[220:223], v[6:9]
	v_mfma_f32_16x16x32_bf16 v[2:5], v[180:183], v[220:223], v[2:5]
	s_setprio 0
	s_barrier
	s_add_i32 s93, s93, 2
	s_add_u32 s0, s0, 0x100
	s_addc_u32 s1, s1, 0
	s_add_u32 s91, s91, 0x100
	s_addc_u32 s92, s92, 0
	s_cmp_gt_u32 s93, 13
	s_cbranch_scc0 .LBB0_322
	s_mov_b32 s100, 1
	s_and_b64 vcc, exec, s[14:15]
	s_cbranch_vccz .LBB0_325
	s_barrier

.LBB0_864:
	s_add_u32 s4, s68, 0xfffc0080
	s_addc_u32 s5, s69, -1
	s_add_i32 s45, 0, 0x10000
	s_cmp_eq_u32 s97, 12
	s_cselect_b32 s75, s57, s5
	s_cselect_b32 s74, s95, s4
	s_cselect_b32 s71, s31, s96
	s_cselect_b32 s70, vcc_lo, vcc_hi
	s_add_i32 s6, 0, 0x14000
	v_add_u32_e32 v104, s45, v239
	v_add_u32_e32 v128, s6, v239
	ds_read_b128 v[90:93], v104
	ds_read_b128 v[94:97], v104 offset:1024
	ds_read_b128 v[100:103], v104 offset:2048
	ds_read_b128 v[104:107], v104 offset:3072
	ds_read_b128 v[108:111], v128
	ds_read_b128 v[112:115], v128 offset:1024
	ds_read_b128 v[120:123], v128 offset:2048
	ds_read_b128 v[128:131], v128 offset:3072
	s_add_i32 s44, s91, 0
	v_lshl_add_u64 v[200:201], s[68:69], 0, v[98:99]
	s_add_i32 m0, s44, 0xc000
	ds_read_b128 v[164:167], v241
	ds_read_b128 v[168:171], v241 offset:1024
	ds_read_b128 v[172:175], v241 offset:2048
	ds_read_b128 v[176:179], v241 offset:3072
	ds_read_b128 v[180:183], v241 offset:4096
	ds_read_b128 v[184:187], v241 offset:5120
	ds_read_b128 v[188:191], v241 offset:6144
	ds_read_b128 v[192:195], v241 offset:7168
	global_load_lds_dwordx4 v[200:201], off
	v_lshl_add_u64 v[200:201], s[68:69], 0, v[206:207]
	s_add_i32 m0, s44, 0xe000
	s_nop 0
	global_load_lds_dwordx4 v[200:201], off
	s_waitcnt vmcnt(8)
	s_waitcnt lgkmcnt(0)
	s_setprio 1
	s_barrier
	v_mfma_f32_16x16x32_bf16 v[160:163], v[90:93], v[164:167], v[160:163]
	v_mfma_f32_16x16x32_bf16 v[156:159], v[100:103], v[164:167], v[156:159]
	v_mfma_f32_16x16x32_bf16 v[144:147], v[90:93], v[172:175], v[144:147]
	v_mfma_f32_16x16x32_bf16 v[140:143], v[100:103], v[172:175], v[140:143]
	v_mfma_f32_16x16x32_bf16 v[124:127], v[90:93], v[180:183], v[124:127]
	v_mfma_f32_16x16x32_bf16 v[116:119], v[100:103], v[180:183], v[116:119]
	v_mfma_f32_16x16x32_bf16 v[78:81], v[90:93], v[188:191], v[78:81]
	v_mfma_f32_16x16x32_bf16 v[74:77], v[100:103], v[188:191], v[74:77]
	v_mfma_f32_16x16x32_bf16 v[160:163], v[94:97], v[168:171], v[160:163]
	v_mfma_f32_16x16x32_bf16 v[156:159], v[104:107], v[168:171], v[156:159]
	v_mfma_f32_16x16x32_bf16 v[144:147], v[94:97], v[176:179], v[144:147]
	v_mfma_f32_16x16x32_bf16 v[140:143], v[104:107], v[176:179], v[140:143]
	v_mfma_f32_16x16x32_bf16 v[124:127], v[94:97], v[184:187], v[124:127]
	v_mfma_f32_16x16x32_bf16 v[116:119], v[104:107], v[184:187], v[116:119]
	v_mfma_f32_16x16x32_bf16 v[78:81], v[94:97], v[192:195], v[78:81]
	v_mfma_f32_16x16x32_bf16 v[74:77], v[104:107], v[192:195], v[74:77]
	s_setprio 0
	s_setprio 1
	v_mfma_f32_16x16x32_bf16 v[152:155], v[108:111], v[164:167], v[152:155]
	v_mfma_f32_16x16x32_bf16 v[148:151], v[120:123], v[164:167], v[148:151]
	v_mfma_f32_16x16x32_bf16 v[136:139], v[108:111], v[172:175], v[136:139]
	v_mfma_f32_16x16x32_bf16 v[132:135], v[120:123], v[172:175], v[132:135]
	v_mfma_f32_16x16x32_bf16 v[86:89], v[108:111], v[180:183], v[86:89]
	v_mfma_f32_16x16x32_bf16 v[82:85], v[120:123], v[180:183], v[82:85]
	v_mfma_f32_16x16x32_bf16 v[70:73], v[108:111], v[188:191], v[70:73]
	v_mfma_f32_16x16x32_bf16 v[66:69], v[120:123], v[188:191], v[66:69]
	v_mfma_f32_16x16x32_bf16 v[152:155], v[112:115], v[168:171], v[152:155]
	v_mfma_f32_16x16x32_bf16 v[148:151], v[128:131], v[168:171], v[148:151]
	v_mfma_f32_16x16x32_bf16 v[136:139], v[112:115], v[176:179], v[136:139]
	v_mfma_f32_16x16x32_bf16 v[132:135], v[128:131], v[176:179], v[132:135]
	v_mfma_f32_16x16x32_bf16 v[86:89], v[112:115], v[184:187], v[86:89]
	v_mfma_f32_16x16x32_bf16 v[82:85], v[128:131], v[184:187], v[82:85]
	v_mfma_f32_16x16x32_bf16 v[70:73], v[112:115], v[192:195], v[70:73]
	v_mfma_f32_16x16x32_bf16 v[66:69], v[128:131], v[192:195], v[66:69]
	s_setprio 0
	s_barrier
	s_add_i32 s4, s45, s91
	v_lshl_add_u64 v[200:201], s[70:71], 0, v[204:205]
	s_mov_b32 m0, s4
	ds_read_b128 v[164:167], v241 offset:16384
	ds_read_b128 v[168:171], v241 offset:17408
	ds_read_b128 v[172:175], v241 offset:18432
	ds_read_b128 v[176:179], v241 offset:19456
	ds_read_b128 v[180:183], v241 offset:20480
	ds_read_b128 v[184:187], v241 offset:21504
	ds_read_b128 v[188:191], v241 offset:22528
	ds_read_b128 v[192:195], v241 offset:23552
	global_load_lds_dwordx4 v[200:201], off
	s_add_i32 m0, s4, 0x2000
	s_add_u32 s4, s70, 0x40000
	v_lshl_add_u64 v[202:203], s[70:71], 0, v[208:209]
	s_addc_u32 s5, s71, 0
	s_add_i32 s6, s6, s91
	global_load_lds_dwordx4 v[202:203], off
	v_lshl_add_u64 v[210:211], s[4:5], 0, v[204:205]
	s_mov_b32 m0, s6
	v_lshl_add_u64 v[212:213], s[74:75], 0, v[206:207]
	global_load_lds_dwordx4 v[210:211], off
	v_lshl_add_u64 v[210:211], s[4:5], 0, v[208:209]
	s_add_i32 m0, s6, 0x2000
	s_nop 0
	global_load_lds_dwordx4 v[210:211], off
	v_lshl_add_u64 v[210:211], s[74:75], 0, v[98:99]
	s_mov_b32 m0, s44
	s_nop 0
	global_load_lds_dwordx4 v[210:211], off
	s_add_i32 m0, s44, 0x2000
	s_nop 0
	global_load_lds_dwordx4 v[212:213], off
	s_waitcnt vmcnt(8)
	s_waitcnt lgkmcnt(0)
	s_setprio 1
	s_barrier
	v_mfma_f32_16x16x32_bf16 v[62:65], v[90:93], v[164:167], v[62:65]
	v_mfma_f32_16x16x32_bf16 v[58:61], v[100:103], v[164:167], v[58:61]
	v_mfma_f32_16x16x32_bf16 v[46:49], v[90:93], v[172:175], v[46:49]
	v_mfma_f32_16x16x32_bf16 v[42:45], v[100:103], v[172:175], v[42:45]
	v_mfma_f32_16x16x32_bf16 v[30:33], v[90:93], v[180:183], v[30:33]
	v_mfma_f32_16x16x32_bf16 v[26:29], v[100:103], v[180:183], v[26:29]
	v_mfma_f32_16x16x32_bf16 v[14:17], v[90:93], v[188:191], v[14:17]
	v_mfma_f32_16x16x32_bf16 v[10:13], v[100:103], v[188:191], v[10:13]
	v_mfma_f32_16x16x32_bf16 v[62:65], v[94:97], v[168:171], v[62:65]
	v_mfma_f32_16x16x32_bf16 v[58:61], v[104:107], v[168:171], v[58:61]
	v_mfma_f32_16x16x32_bf16 v[46:49], v[94:97], v[176:179], v[46:49]
	v_mfma_f32_16x16x32_bf16 v[42:45], v[104:107], v[176:179], v[42:45]
	v_mfma_f32_16x16x32_bf16 v[30:33], v[94:97], v[184:187], v[30:33]
	v_mfma_f32_16x16x32_bf16 v[26:29], v[104:107], v[184:187], v[26:29]
	v_mfma_f32_16x16x32_bf16 v[14:17], v[94:97], v[192:195], v[14:17]
	v_mfma_f32_16x16x32_bf16 v[10:13], v[104:107], v[192:195], v[10:13]
	s_setprio 0
	s_setprio 1
	v_mfma_f32_16x16x32_bf16 v[54:57], v[108:111], v[164:167], v[54:57]
	v_mfma_f32_16x16x32_bf16 v[50:53], v[120:123], v[164:167], v[50:53]
	v_mfma_f32_16x16x32_bf16 v[38:41], v[108:111], v[172:175], v[38:41]
	v_mfma_f32_16x16x32_bf16 v[34:37], v[120:123], v[172:175], v[34:37]
	v_mfma_f32_16x16x32_bf16 v[22:25], v[108:111], v[180:183], v[22:25]
	v_mfma_f32_16x16x32_bf16 v[18:21], v[120:123], v[180:183], v[18:21]
	v_mfma_f32_16x16x32_bf16 v[6:9], v[108:111], v[188:191], v[6:9]
	v_mfma_f32_16x16x32_bf16 v[2:5], v[120:123], v[188:191], v[2:5]
	v_mfma_f32_16x16x32_bf16 v[54:57], v[112:115], v[168:171], v[54:57]
	v_mfma_f32_16x16x32_bf16 v[50:53], v[128:131], v[168:171], v[50:53]
	v_mfma_f32_16x16x32_bf16 v[38:41], v[112:115], v[176:179], v[38:41]
	v_mfma_f32_16x16x32_bf16 v[34:37], v[128:131], v[176:179], v[34:37]
	v_mfma_f32_16x16x32_bf16 v[22:25], v[112:115], v[184:187], v[22:25]
	v_mfma_f32_16x16x32_bf16 v[18:21], v[128:131], v[184:187], v[18:21]
	v_mfma_f32_16x16x32_bf16 v[6:9], v[112:115], v[192:195], v[6:9]
	v_mfma_f32_16x16x32_bf16 v[2:5], v[128:131], v[192:195], v[2:5]
	s_setprio 0
	s_barrier
	s_add_i32 s6, 0, 0x18000
	s_add_i32 s7, 0, 0x1c000
	v_add_u32_e32 v104, s6, v239
	v_add_u32_e32 v128, s7, v239
	ds_read_b128 v[90:93], v104
	ds_read_b128 v[94:97], v104 offset:1024
	ds_read_b128 v[100:103], v104 offset:2048
	ds_read_b128 v[104:107], v104 offset:3072
	ds_read_b128 v[108:111], v128
	ds_read_b128 v[112:115], v128 offset:1024
	ds_read_b128 v[120:123], v128 offset:2048
	ds_read_b128 v[128:131], v128 offset:3072
	s_add_u32 s4, s74, 0x40000
	s_addc_u32 s5, s75, 0
	v_lshl_add_u64 v[214:215], s[4:5], 0, v[98:99]
	s_add_i32 m0, s44, 0x4000
	ds_read_b128 v[164:167], v241 offset:32768
	ds_read_b128 v[168:171], v241 offset:33792
	ds_read_b128 v[172:175], v241 offset:34816
	ds_read_b128 v[176:179], v241 offset:35840
	ds_read_b128 v[180:183], v241 offset:36864
	ds_read_b128 v[184:187], v241 offset:37888
	ds_read_b128 v[188:191], v241 offset:38912
	ds_read_b128 v[192:195], v241 offset:39936
	global_load_lds_dwordx4 v[214:215], off
	v_lshl_add_u64 v[214:215], s[4:5], 0, v[206:207]
	s_add_i32 m0, s44, 0x6000
	s_nop 0
	global_load_lds_dwordx4 v[214:215], off
	s_waitcnt vmcnt(8)
	s_waitcnt lgkmcnt(0)
	s_setprio 1
	s_barrier
	v_mfma_f32_16x16x32_bf16 v[160:163], v[90:93], v[164:167], v[160:163]
	v_mfma_f32_16x16x32_bf16 v[156:159], v[100:103], v[164:167], v[156:159]
	v_mfma_f32_16x16x32_bf16 v[144:147], v[90:93], v[172:175], v[144:147]
	v_mfma_f32_16x16x32_bf16 v[140:143], v[100:103], v[172:175], v[140:143]
	v_mfma_f32_16x16x32_bf16 v[124:127], v[90:93], v[180:183], v[124:127]
	v_mfma_f32_16x16x32_bf16 v[116:119], v[100:103], v[180:183], v[116:119]
	v_mfma_f32_16x16x32_bf16 v[78:81], v[90:93], v[188:191], v[78:81]
	v_mfma_f32_16x16x32_bf16 v[74:77], v[100:103], v[188:191], v[74:77]
	v_mfma_f32_16x16x32_bf16 v[160:163], v[94:97], v[168:171], v[160:163]
	v_mfma_f32_16x16x32_bf16 v[156:159], v[104:107], v[168:171], v[156:159]
	v_mfma_f32_16x16x32_bf16 v[144:147], v[94:97], v[176:179], v[144:147]
	v_mfma_f32_16x16x32_bf16 v[140:143], v[104:107], v[176:179], v[140:143]
	v_mfma_f32_16x16x32_bf16 v[124:127], v[94:97], v[184:187], v[124:127]
	v_mfma_f32_16x16x32_bf16 v[116:119], v[104:107], v[184:187], v[116:119]
	v_mfma_f32_16x16x32_bf16 v[78:81], v[94:97], v[192:195], v[78:81]
	v_mfma_f32_16x16x32_bf16 v[74:77], v[104:107], v[192:195], v[74:77]
	s_setprio 0
	s_setprio 1
	v_mfma_f32_16x16x32_bf16 v[152:155], v[108:111], v[164:167], v[152:155]
	v_mfma_f32_16x16x32_bf16 v[148:151], v[120:123], v[164:167], v[148:151]
	v_mfma_f32_16x16x32_bf16 v[136:139], v[108:111], v[172:175], v[136:139]
	v_mfma_f32_16x16x32_bf16 v[132:135], v[120:123], v[172:175], v[132:135]
	v_mfma_f32_16x16x32_bf16 v[86:89], v[108:111], v[180:183], v[86:89]
	v_mfma_f32_16x16x32_bf16 v[82:85], v[120:123], v[180:183], v[82:85]
	v_mfma_f32_16x16x32_bf16 v[70:73], v[108:111], v[188:191], v[70:73]
	v_mfma_f32_16x16x32_bf16 v[66:69], v[120:123], v[188:191], v[66:69]
	v_mfma_f32_16x16x32_bf16 v[152:155], v[112:115], v[168:171], v[152:155]
	v_mfma_f32_16x16x32_bf16 v[148:151], v[128:131], v[168:171], v[148:151]
	v_mfma_f32_16x16x32_bf16 v[136:139], v[112:115], v[176:179], v[136:139]
	v_mfma_f32_16x16x32_bf16 v[132:135], v[128:131], v[176:179], v[132:135]
	v_mfma_f32_16x16x32_bf16 v[86:89], v[112:115], v[184:187], v[86:89]
	v_mfma_f32_16x16x32_bf16 v[82:85], v[128:131], v[184:187], v[82:85]
	v_mfma_f32_16x16x32_bf16 v[70:73], v[112:115], v[192:195], v[70:73]
	v_mfma_f32_16x16x32_bf16 v[66:69], v[128:131], v[192:195], v[66:69]
	s_setprio 0
	s_barrier
	s_add_i32 s4, s6, s91
	v_lshl_add_u64 v[200:201], v[200:201], 0, s[42:43]
	s_mov_b32 m0, s4
	ds_read_b128 v[164:167], v241 offset:49152
	ds_read_b128 v[168:171], v241 offset:50176
	ds_read_b128 v[172:175], v241 offset:51200
	ds_read_b128 v[176:179], v241 offset:52224
	ds_read_b128 v[180:183], v241 offset:53248
	ds_read_b128 v[184:187], v241 offset:54272
	ds_read_b128 v[188:191], v241 offset:55296
	ds_read_b128 v[192:195], v241 offset:56320
	global_load_lds_dwordx4 v[200:201], off
	s_add_i32 m0, s4, 0x2000
	s_add_u32 s4, s70, 0x40080
	v_lshl_add_u64 v[200:201], v[202:203], 0, s[42:43]
	s_addc_u32 s5, s71, 0
	s_add_i32 s6, s7, s91
	global_load_lds_dwordx4 v[200:201], off
	v_lshl_add_u64 v[200:201], s[4:5], 0, v[204:205]
	s_mov_b32 m0, s6
	s_nop 0
	global_load_lds_dwordx4 v[200:201], off
	v_lshl_add_u64 v[200:201], s[4:5], 0, v[208:209]
	s_add_i32 m0, s6, 0x2000
	s_nop 0
	global_load_lds_dwordx4 v[200:201], off
	v_lshl_add_u64 v[200:201], v[210:211], 0, s[42:43]
	s_add_i32 m0, s44, 0x8000
	s_nop 0
	global_load_lds_dwordx4 v[200:201], off
	v_lshl_add_u64 v[200:201], v[212:213], 0, s[42:43]
	s_add_i32 m0, s44, 0xa000
	s_nop 0
	global_load_lds_dwordx4 v[200:201], off
	s_waitcnt vmcnt(8)
	s_waitcnt lgkmcnt(0)
	s_setprio 1
	s_barrier
	v_mfma_f32_16x16x32_bf16 v[62:65], v[90:93], v[164:167], v[62:65]
	v_mfma_f32_16x16x32_bf16 v[58:61], v[100:103], v[164:167], v[58:61]
	v_mfma_f32_16x16x32_bf16 v[46:49], v[90:93], v[172:175], v[46:49]
	v_mfma_f32_16x16x32_bf16 v[42:45], v[100:103], v[172:175], v[42:45]
	v_mfma_f32_16x16x32_bf16 v[30:33], v[90:93], v[180:183], v[30:33]
	v_mfma_f32_16x16x32_bf16 v[26:29], v[100:103], v[180:183], v[26:29]
	v_mfma_f32_16x16x32_bf16 v[14:17], v[90:93], v[188:191], v[14:17]
	v_mfma_f32_16x16x32_bf16 v[10:13], v[100:103], v[188:191], v[10:13]
	v_mfma_f32_16x16x32_bf16 v[62:65], v[94:97], v[168:171], v[62:65]
	v_mfma_f32_16x16x32_bf16 v[58:61], v[104:107], v[168:171], v[58:61]
	v_mfma_f32_16x16x32_bf16 v[46:49], v[94:97], v[176:179], v[46:49]
	v_mfma_f32_16x16x32_bf16 v[42:45], v[104:107], v[176:179], v[42:45]
	v_mfma_f32_16x16x32_bf16 v[30:33], v[94:97], v[184:187], v[30:33]
	v_mfma_f32_16x16x32_bf16 v[26:29], v[104:107], v[184:187], v[26:29]
	v_mfma_f32_16x16x32_bf16 v[14:17], v[94:97], v[192:195], v[14:17]
	v_mfma_f32_16x16x32_bf16 v[10:13], v[104:107], v[192:195], v[10:13]
	s_setprio 0
	s_setprio 1
	v_mfma_f32_16x16x32_bf16 v[54:57], v[108:111], v[164:167], v[54:57]
	v_mfma_f32_16x16x32_bf16 v[50:53], v[120:123], v[164:167], v[50:53]
	v_mfma_f32_16x16x32_bf16 v[38:41], v[108:111], v[172:175], v[38:41]
	v_mfma_f32_16x16x32_bf16 v[34:37], v[120:123], v[172:175], v[34:37]
	v_mfma_f32_16x16x32_bf16 v[22:25], v[108:111], v[180:183], v[22:25]
	v_mfma_f32_16x16x32_bf16 v[18:21], v[120:123], v[180:183], v[18:21]
	v_mfma_f32_16x16x32_bf16 v[6:9], v[108:111], v[188:191], v[6:9]
	v_mfma_f32_16x16x32_bf16 v[2:5], v[120:123], v[188:191], v[2:5]
	v_mfma_f32_16x16x32_bf16 v[54:57], v[112:115], v[168:171], v[54:57]
	v_mfma_f32_16x16x32_bf16 v[50:53], v[128:131], v[168:171], v[50:53]
	v_mfma_f32_16x16x32_bf16 v[38:41], v[112:115], v[176:179], v[38:41]
	v_mfma_f32_16x16x32_bf16 v[34:37], v[128:131], v[176:179], v[34:37]
	v_mfma_f32_16x16x32_bf16 v[22:25], v[112:115], v[184:187], v[22:25]
	v_mfma_f32_16x16x32_bf16 v[18:21], v[128:131], v[184:187], v[18:21]
	v_mfma_f32_16x16x32_bf16 v[6:9], v[112:115], v[192:195], v[6:9]
	v_mfma_f32_16x16x32_bf16 v[2:5], v[128:131], v[192:195], v[2:5]
	s_setprio 0
	s_barrier
	s_add_i32 s97, s97, 2
	s_add_u32 s68, s68, 0x100
	s_addc_u32 s69, s69, 0
	s_add_u32 vcc_hi, vcc_hi, 0x100
	s_addc_u32 s96, s96, 0
	s_cmp_gt_u32 s97, 13
	s_cbranch_scc0 .LBB0_864
	s_mov_b32 s100, 1
	s_and_b64 vcc, exec, s[12:13]
	s_cbranch_vccz .LBB0_867
	s_barrier

.LBB0_908:
	s_add_u32 s4, s56, 0xfffc0080
	s_addc_u32 s5, s57, -1
	s_add_i32 s45, 0, 0x10000
	s_cmp_eq_u32 s96, 12
	s_cselect_b32 s71, s21, s5
	s_cselect_b32 s70, s93, s4
	s_cselect_b32 s69, s15, vcc_lo
	s_cselect_b32 s68, s94, s95
	s_add_i32 s97, 0, 0x14000
	v_add_u32_e32 v104, s45, v223
	v_add_u32_e32 v124, s97, v223
	ds_read_b128 v[86:89], v104
	ds_read_b128 v[90:93], v104 offset:1024
	ds_read_b128 v[100:103], v104 offset:2048
	ds_read_b128 v[104:107], v104 offset:3072
	ds_read_b128 v[108:111], v124
	ds_read_b128 v[112:115], v124 offset:1024
	ds_read_b128 v[116:119], v124 offset:2048
	ds_read_b128 v[124:127], v124 offset:3072
	s_add_i32 s44, s74, 0
	v_lshl_add_u64 v[200:201], s[56:57], 0, v[98:99]
	s_add_i32 m0, s44, 0xc000
	ds_read_b128 v[164:167], v225
	ds_read_b128 v[168:171], v225 offset:1024
	ds_read_b128 v[172:175], v225 offset:2048
	ds_read_b128 v[176:179], v225 offset:3072
	ds_read_b128 v[180:183], v225 offset:4096
	ds_read_b128 v[184:187], v225 offset:5120
	ds_read_b128 v[188:191], v225 offset:6144
	ds_read_b128 v[192:195], v225 offset:7168
	global_load_lds_dwordx4 v[200:201], off
	v_lshl_add_u64 v[200:201], s[56:57], 0, v[206:207]
	s_add_i32 m0, s44, 0xe000
	s_nop 0
	global_load_lds_dwordx4 v[200:201], off
	s_waitcnt vmcnt(8)
	s_waitcnt lgkmcnt(0)
	s_setprio 1
	s_barrier
	v_mfma_f32_16x16x32_bf16 v[160:163], v[86:89], v[164:167], v[160:163]
	v_mfma_f32_16x16x32_bf16 v[156:159], v[100:103], v[164:167], v[156:159]
	v_mfma_f32_16x16x32_bf16 v[144:147], v[86:89], v[172:175], v[144:147]
	v_mfma_f32_16x16x32_bf16 v[140:143], v[100:103], v[172:175], v[140:143]
	v_mfma_f32_16x16x32_bf16 v[128:131], v[86:89], v[180:183], v[128:131]
	v_mfma_f32_16x16x32_bf16 v[120:123], v[100:103], v[180:183], v[120:123]
	v_mfma_f32_16x16x32_bf16 v[78:81], v[86:89], v[188:191], v[78:81]
	v_mfma_f32_16x16x32_bf16 v[74:77], v[100:103], v[188:191], v[74:77]
	v_mfma_f32_16x16x32_bf16 v[160:163], v[90:93], v[168:171], v[160:163]
	v_mfma_f32_16x16x32_bf16 v[156:159], v[104:107], v[168:171], v[156:159]
	v_mfma_f32_16x16x32_bf16 v[144:147], v[90:93], v[176:179], v[144:147]
	v_mfma_f32_16x16x32_bf16 v[140:143], v[104:107], v[176:179], v[140:143]
	v_mfma_f32_16x16x32_bf16 v[128:131], v[90:93], v[184:187], v[128:131]
	v_mfma_f32_16x16x32_bf16 v[120:123], v[104:107], v[184:187], v[120:123]
	v_mfma_f32_16x16x32_bf16 v[78:81], v[90:93], v[192:195], v[78:81]
	v_mfma_f32_16x16x32_bf16 v[74:77], v[104:107], v[192:195], v[74:77]
	s_setprio 0
	s_setprio 1
	v_mfma_f32_16x16x32_bf16 v[152:155], v[108:111], v[164:167], v[152:155]
	v_mfma_f32_16x16x32_bf16 v[148:151], v[116:119], v[164:167], v[148:151]
	v_mfma_f32_16x16x32_bf16 v[136:139], v[108:111], v[172:175], v[136:139]
	v_mfma_f32_16x16x32_bf16 v[132:135], v[116:119], v[172:175], v[132:135]
	v_mfma_f32_16x16x32_bf16 v[94:97], v[108:111], v[180:183], v[94:97]
	v_mfma_f32_16x16x32_bf16 v[82:85], v[116:119], v[180:183], v[82:85]
	v_mfma_f32_16x16x32_bf16 v[70:73], v[108:111], v[188:191], v[70:73]
	v_mfma_f32_16x16x32_bf16 v[66:69], v[116:119], v[188:191], v[66:69]
	v_mfma_f32_16x16x32_bf16 v[152:155], v[112:115], v[168:171], v[152:155]
	v_mfma_f32_16x16x32_bf16 v[148:151], v[124:127], v[168:171], v[148:151]
	v_mfma_f32_16x16x32_bf16 v[136:139], v[112:115], v[176:179], v[136:139]
	v_mfma_f32_16x16x32_bf16 v[132:135], v[124:127], v[176:179], v[132:135]
	v_mfma_f32_16x16x32_bf16 v[94:97], v[112:115], v[184:187], v[94:97]
	v_mfma_f32_16x16x32_bf16 v[82:85], v[124:127], v[184:187], v[82:85]
	v_mfma_f32_16x16x32_bf16 v[70:73], v[112:115], v[192:195], v[70:73]
	v_mfma_f32_16x16x32_bf16 v[66:69], v[124:127], v[192:195], v[66:69]
	s_setprio 0
	s_barrier
	s_add_i32 s4, s45, s74
	v_lshl_add_u64 v[200:201], s[68:69], 0, v[204:205]
	s_mov_b32 m0, s4
	ds_read_b128 v[164:167], v225 offset:16384
	ds_read_b128 v[168:171], v225 offset:17408
	ds_read_b128 v[172:175], v225 offset:18432
	ds_read_b128 v[176:179], v225 offset:19456
	ds_read_b128 v[180:183], v225 offset:20480
	ds_read_b128 v[184:187], v225 offset:21504
	ds_read_b128 v[188:191], v225 offset:22528
	ds_read_b128 v[192:195], v225 offset:23552
	global_load_lds_dwordx4 v[200:201], off
	s_add_i32 m0, s4, 0x2000
	s_add_u32 s4, s68, 0x40000
	v_lshl_add_u64 v[202:203], s[68:69], 0, v[208:209]
	s_addc_u32 s5, s69, 0
	s_add_i32 s45, s97, s74
	global_load_lds_dwordx4 v[202:203], off
	v_lshl_add_u64 v[210:211], s[4:5], 0, v[204:205]
	s_mov_b32 m0, s45
	v_lshl_add_u64 v[212:213], s[70:71], 0, v[206:207]
	global_load_lds_dwordx4 v[210:211], off
	v_lshl_add_u64 v[210:211], s[4:5], 0, v[208:209]
	s_add_i32 m0, s45, 0x2000
	s_nop 0
	global_load_lds_dwordx4 v[210:211], off
	v_lshl_add_u64 v[210:211], s[70:71], 0, v[98:99]
	s_mov_b32 m0, s44
	s_nop 0
	global_load_lds_dwordx4 v[210:211], off
	s_add_i32 m0, s44, 0x2000
	s_nop 0
	global_load_lds_dwordx4 v[212:213], off
	s_waitcnt vmcnt(8)
	s_waitcnt lgkmcnt(0)
	s_setprio 1
	s_barrier
	v_mfma_f32_16x16x32_bf16 v[62:65], v[86:89], v[164:167], v[62:65]
	v_mfma_f32_16x16x32_bf16 v[58:61], v[100:103], v[164:167], v[58:61]
	v_mfma_f32_16x16x32_bf16 v[46:49], v[86:89], v[172:175], v[46:49]
	v_mfma_f32_16x16x32_bf16 v[42:45], v[100:103], v[172:175], v[42:45]
	v_mfma_f32_16x16x32_bf16 v[30:33], v[86:89], v[180:183], v[30:33]
	v_mfma_f32_16x16x32_bf16 v[26:29], v[100:103], v[180:183], v[26:29]
	v_mfma_f32_16x16x32_bf16 v[14:17], v[86:89], v[188:191], v[14:17]
	v_mfma_f32_16x16x32_bf16 v[10:13], v[100:103], v[188:191], v[10:13]
	v_mfma_f32_16x16x32_bf16 v[62:65], v[90:93], v[168:171], v[62:65]
	v_mfma_f32_16x16x32_bf16 v[58:61], v[104:107], v[168:171], v[58:61]
	v_mfma_f32_16x16x32_bf16 v[46:49], v[90:93], v[176:179], v[46:49]
	v_mfma_f32_16x16x32_bf16 v[42:45], v[104:107], v[176:179], v[42:45]
	v_mfma_f32_16x16x32_bf16 v[30:33], v[90:93], v[184:187], v[30:33]
	v_mfma_f32_16x16x32_bf16 v[26:29], v[104:107], v[184:187], v[26:29]
	v_mfma_f32_16x16x32_bf16 v[14:17], v[90:93], v[192:195], v[14:17]
	v_mfma_f32_16x16x32_bf16 v[10:13], v[104:107], v[192:195], v[10:13]
	s_setprio 0
	s_setprio 1
	v_mfma_f32_16x16x32_bf16 v[54:57], v[108:111], v[164:167], v[54:57]
	v_mfma_f32_16x16x32_bf16 v[50:53], v[116:119], v[164:167], v[50:53]
	v_mfma_f32_16x16x32_bf16 v[38:41], v[108:111], v[172:175], v[38:41]
	v_mfma_f32_16x16x32_bf16 v[34:37], v[116:119], v[172:175], v[34:37]
	v_mfma_f32_16x16x32_bf16 v[22:25], v[108:111], v[180:183], v[22:25]
	v_mfma_f32_16x16x32_bf16 v[18:21], v[116:119], v[180:183], v[18:21]
	v_mfma_f32_16x16x32_bf16 v[6:9], v[108:111], v[188:191], v[6:9]
	v_mfma_f32_16x16x32_bf16 v[2:5], v[116:119], v[188:191], v[2:5]
	v_mfma_f32_16x16x32_bf16 v[54:57], v[112:115], v[168:171], v[54:57]
	v_mfma_f32_16x16x32_bf16 v[50:53], v[124:127], v[168:171], v[50:53]
	v_mfma_f32_16x16x32_bf16 v[38:41], v[112:115], v[176:179], v[38:41]
	v_mfma_f32_16x16x32_bf16 v[34:37], v[124:127], v[176:179], v[34:37]
	v_mfma_f32_16x16x32_bf16 v[22:25], v[112:115], v[184:187], v[22:25]
	v_mfma_f32_16x16x32_bf16 v[18:21], v[124:127], v[184:187], v[18:21]
	v_mfma_f32_16x16x32_bf16 v[6:9], v[112:115], v[192:195], v[6:9]
	v_mfma_f32_16x16x32_bf16 v[2:5], v[124:127], v[192:195], v[2:5]
	s_setprio 0
	s_barrier
	s_add_i32 s45, 0, 0x18000
	s_add_i32 s97, 0, 0x1c000
	v_add_u32_e32 v104, s45, v223
	v_add_u32_e32 v124, s97, v223
	ds_read_b128 v[86:89], v104
	ds_read_b128 v[90:93], v104 offset:1024
	ds_read_b128 v[100:103], v104 offset:2048
	ds_read_b128 v[104:107], v104 offset:3072
	ds_read_b128 v[108:111], v124
	ds_read_b128 v[112:115], v124 offset:1024
	ds_read_b128 v[116:119], v124 offset:2048
	ds_read_b128 v[124:127], v124 offset:3072
	s_add_u32 s4, s70, 0x40000
	s_addc_u32 s5, s71, 0
	v_lshl_add_u64 v[214:215], s[4:5], 0, v[98:99]
	s_add_i32 m0, s44, 0x4000
	ds_read_b128 v[164:167], v225 offset:32768
	ds_read_b128 v[168:171], v225 offset:33792
	ds_read_b128 v[172:175], v225 offset:34816
	ds_read_b128 v[176:179], v225 offset:35840
	ds_read_b128 v[180:183], v225 offset:36864
	ds_read_b128 v[184:187], v225 offset:37888
	ds_read_b128 v[188:191], v225 offset:38912
	ds_read_b128 v[192:195], v225 offset:39936
	global_load_lds_dwordx4 v[214:215], off
	v_lshl_add_u64 v[214:215], s[4:5], 0, v[206:207]
	s_add_i32 m0, s44, 0x6000
	s_nop 0
	global_load_lds_dwordx4 v[214:215], off
	s_waitcnt vmcnt(8)
	s_waitcnt lgkmcnt(0)
	s_setprio 1
	s_barrier
	v_mfma_f32_16x16x32_bf16 v[160:163], v[86:89], v[164:167], v[160:163]
	v_mfma_f32_16x16x32_bf16 v[156:159], v[100:103], v[164:167], v[156:159]
	v_mfma_f32_16x16x32_bf16 v[144:147], v[86:89], v[172:175], v[144:147]
	v_mfma_f32_16x16x32_bf16 v[140:143], v[100:103], v[172:175], v[140:143]
	v_mfma_f32_16x16x32_bf16 v[128:131], v[86:89], v[180:183], v[128:131]
	v_mfma_f32_16x16x32_bf16 v[120:123], v[100:103], v[180:183], v[120:123]
	v_mfma_f32_16x16x32_bf16 v[78:81], v[86:89], v[188:191], v[78:81]
	v_mfma_f32_16x16x32_bf16 v[74:77], v[100:103], v[188:191], v[74:77]
	v_mfma_f32_16x16x32_bf16 v[160:163], v[90:93], v[168:171], v[160:163]
	v_mfma_f32_16x16x32_bf16 v[156:159], v[104:107], v[168:171], v[156:159]
	v_mfma_f32_16x16x32_bf16 v[144:147], v[90:93], v[176:179], v[144:147]
	v_mfma_f32_16x16x32_bf16 v[140:143], v[104:107], v[176:179], v[140:143]
	v_mfma_f32_16x16x32_bf16 v[128:131], v[90:93], v[184:187], v[128:131]
	v_mfma_f32_16x16x32_bf16 v[120:123], v[104:107], v[184:187], v[120:123]
	v_mfma_f32_16x16x32_bf16 v[78:81], v[90:93], v[192:195], v[78:81]
	v_mfma_f32_16x16x32_bf16 v[74:77], v[104:107], v[192:195], v[74:77]
	s_setprio 0
	s_setprio 1
	v_mfma_f32_16x16x32_bf16 v[152:155], v[108:111], v[164:167], v[152:155]
	v_mfma_f32_16x16x32_bf16 v[148:151], v[116:119], v[164:167], v[148:151]
	v_mfma_f32_16x16x32_bf16 v[136:139], v[108:111], v[172:175], v[136:139]
	v_mfma_f32_16x16x32_bf16 v[132:135], v[116:119], v[172:175], v[132:135]
	v_mfma_f32_16x16x32_bf16 v[94:97], v[108:111], v[180:183], v[94:97]
	v_mfma_f32_16x16x32_bf16 v[82:85], v[116:119], v[180:183], v[82:85]
	v_mfma_f32_16x16x32_bf16 v[70:73], v[108:111], v[188:191], v[70:73]
	v_mfma_f32_16x16x32_bf16 v[66:69], v[116:119], v[188:191], v[66:69]
	v_mfma_f32_16x16x32_bf16 v[152:155], v[112:115], v[168:171], v[152:155]
	v_mfma_f32_16x16x32_bf16 v[148:151], v[124:127], v[168:171], v[148:151]
	v_mfma_f32_16x16x32_bf16 v[136:139], v[112:115], v[176:179], v[136:139]
	v_mfma_f32_16x16x32_bf16 v[132:135], v[124:127], v[176:179], v[132:135]
	v_mfma_f32_16x16x32_bf16 v[94:97], v[112:115], v[184:187], v[94:97]
	v_mfma_f32_16x16x32_bf16 v[82:85], v[124:127], v[184:187], v[82:85]
	v_mfma_f32_16x16x32_bf16 v[70:73], v[112:115], v[192:195], v[70:73]
	v_mfma_f32_16x16x32_bf16 v[66:69], v[124:127], v[192:195], v[66:69]
	s_setprio 0
	s_barrier
	s_add_i32 s4, s45, s74
	v_lshl_add_u64 v[200:201], v[200:201], 0, s[42:43]
	s_mov_b32 m0, s4
	ds_read_b128 v[164:167], v225 offset:49152
	ds_read_b128 v[168:171], v225 offset:50176
	ds_read_b128 v[172:175], v225 offset:51200
	ds_read_b128 v[176:179], v225 offset:52224
	ds_read_b128 v[180:183], v225 offset:53248
	ds_read_b128 v[184:187], v225 offset:54272
	ds_read_b128 v[188:191], v225 offset:55296
	ds_read_b128 v[192:195], v225 offset:56320
	global_load_lds_dwordx4 v[200:201], off
	s_add_i32 m0, s4, 0x2000
	s_add_u32 s4, s68, 0x40080
	v_lshl_add_u64 v[200:201], v[202:203], 0, s[42:43]
	s_addc_u32 s5, s69, 0
	s_add_i32 s45, s97, s74
	global_load_lds_dwordx4 v[200:201], off
	v_lshl_add_u64 v[200:201], s[4:5], 0, v[204:205]
	s_mov_b32 m0, s45
	s_nop 0
	global_load_lds_dwordx4 v[200:201], off
	v_lshl_add_u64 v[200:201], s[4:5], 0, v[208:209]
	s_add_i32 m0, s45, 0x2000
	s_nop 0
	global_load_lds_dwordx4 v[200:201], off
	v_lshl_add_u64 v[200:201], v[210:211], 0, s[42:43]
	s_add_i32 m0, s44, 0x8000
	s_nop 0
	global_load_lds_dwordx4 v[200:201], off
	v_lshl_add_u64 v[200:201], v[212:213], 0, s[42:43]
	s_add_i32 m0, s44, 0xa000
	s_nop 0
	global_load_lds_dwordx4 v[200:201], off
	s_waitcnt vmcnt(8)
	s_waitcnt lgkmcnt(0)
	s_setprio 1
	s_barrier
	v_mfma_f32_16x16x32_bf16 v[62:65], v[86:89], v[164:167], v[62:65]
	v_mfma_f32_16x16x32_bf16 v[58:61], v[100:103], v[164:167], v[58:61]
	v_mfma_f32_16x16x32_bf16 v[46:49], v[86:89], v[172:175], v[46:49]
	v_mfma_f32_16x16x32_bf16 v[42:45], v[100:103], v[172:175], v[42:45]
	v_mfma_f32_16x16x32_bf16 v[30:33], v[86:89], v[180:183], v[30:33]
	v_mfma_f32_16x16x32_bf16 v[26:29], v[100:103], v[180:183], v[26:29]
	v_mfma_f32_16x16x32_bf16 v[14:17], v[86:89], v[188:191], v[14:17]
	v_mfma_f32_16x16x32_bf16 v[10:13], v[100:103], v[188:191], v[10:13]
	v_mfma_f32_16x16x32_bf16 v[62:65], v[90:93], v[168:171], v[62:65]
	v_mfma_f32_16x16x32_bf16 v[58:61], v[104:107], v[168:171], v[58:61]
	v_mfma_f32_16x16x32_bf16 v[46:49], v[90:93], v[176:179], v[46:49]
	v_mfma_f32_16x16x32_bf16 v[42:45], v[104:107], v[176:179], v[42:45]
	v_mfma_f32_16x16x32_bf16 v[30:33], v[90:93], v[184:187], v[30:33]
	v_mfma_f32_16x16x32_bf16 v[26:29], v[104:107], v[184:187], v[26:29]
	v_mfma_f32_16x16x32_bf16 v[14:17], v[90:93], v[192:195], v[14:17]
	v_mfma_f32_16x16x32_bf16 v[10:13], v[104:107], v[192:195], v[10:13]
	s_setprio 0
	s_setprio 1
	v_mfma_f32_16x16x32_bf16 v[54:57], v[108:111], v[164:167], v[54:57]
	v_mfma_f32_16x16x32_bf16 v[50:53], v[116:119], v[164:167], v[50:53]
	v_mfma_f32_16x16x32_bf16 v[38:41], v[108:111], v[172:175], v[38:41]
	v_mfma_f32_16x16x32_bf16 v[34:37], v[116:119], v[172:175], v[34:37]
	v_mfma_f32_16x16x32_bf16 v[22:25], v[108:111], v[180:183], v[22:25]
	v_mfma_f32_16x16x32_bf16 v[18:21], v[116:119], v[180:183], v[18:21]
	v_mfma_f32_16x16x32_bf16 v[6:9], v[108:111], v[188:191], v[6:9]
	v_mfma_f32_16x16x32_bf16 v[2:5], v[116:119], v[188:191], v[2:5]
	v_mfma_f32_16x16x32_bf16 v[54:57], v[112:115], v[168:171], v[54:57]
	v_mfma_f32_16x16x32_bf16 v[50:53], v[124:127], v[168:171], v[50:53]
	v_mfma_f32_16x16x32_bf16 v[38:41], v[112:115], v[176:179], v[38:41]
	v_mfma_f32_16x16x32_bf16 v[34:37], v[124:127], v[176:179], v[34:37]
	v_mfma_f32_16x16x32_bf16 v[22:25], v[112:115], v[184:187], v[22:25]
	v_mfma_f32_16x16x32_bf16 v[18:21], v[124:127], v[184:187], v[18:21]
	v_mfma_f32_16x16x32_bf16 v[6:9], v[112:115], v[192:195], v[6:9]
	v_mfma_f32_16x16x32_bf16 v[2:5], v[124:127], v[192:195], v[2:5]
	s_setprio 0
	s_barrier
	s_add_i32 s96, s96, 2
	s_add_u32 s56, s56, 0x100
	s_addc_u32 s57, s57, 0
	s_add_u32 s95, s95, 0x100
	s_addc_u32 vcc_lo, vcc_lo, 0
	s_cmp_gt_u32 s96, 13
	s_cbranch_scc0 .LBB0_908
	s_mov_b32 s100, 1
	v_mov_b32_e32 v196, 0x2d00
	v_mov_b32_e32 v231, 0x2400
	v_mov_b32_e32 v228, 0x1b00
	s_and_b64 vcc, exec, s[0:1]
	s_movk_i32 s21, 0x4000
	s_cbranch_vccz .LBB0_911
	s_barrier

.LBB0_1011:
	s_add_u32 s4, s40, 0xfffc0080
	s_addc_u32 s5, s41, -1
	s_add_i32 s6, 0, 0x10000
	s_cmp_eq_u32 s92, 12
	s_cselect_b32 s69, s21, s5
	s_cselect_b32 s68, s88, s4
	s_cselect_b32 s57, s15, s91
	s_cselect_b32 s56, s89, s90
	s_add_i32 s7, 0, 0x14000
	v_add_u32_e32 v144, s6, v189
	v_add_u32_e32 v160, s7, v189
	ds_read_b128 v[132:135], v144
	ds_read_b128 v[136:139], v144 offset:1024
	ds_read_b128 v[140:143], v144 offset:2048
	ds_read_b128 v[144:147], v144 offset:3072
	ds_read_b128 v[156:159], v160
	ds_read_b128 v[162:165], v160 offset:1024
	ds_read_b128 v[192:195], v160 offset:2048
	ds_read_b128 v[200:203], v160 offset:3072
	s_add_i32 s44, s70, 0
	v_lshl_add_u64 v[166:167], s[40:41], 0, v[98:99]
	s_add_i32 m0, s44, 0xc000
	ds_read_b128 v[204:207], v191
	ds_read_b128 v[208:211], v191 offset:1024
	ds_read_b128 v[212:215], v191 offset:2048
	ds_read_b128 v[216:219], v191 offset:3072
	ds_read_b128 v[220:223], v191 offset:4096
	ds_read_b128 v[224:227], v191 offset:5120
	ds_read_b128 v[238:241], v191 offset:6144
	ds_read_b128 v[242:245], v191 offset:7168
	global_load_lds_dwordx4 v[166:167], off
	v_lshl_add_u64 v[166:167], s[40:41], 0, v[150:151]
	s_add_i32 m0, s44, 0xe000
	s_nop 0
	global_load_lds_dwordx4 v[166:167], off
	s_waitcnt vmcnt(8)
	s_waitcnt lgkmcnt(0)
	s_setprio 1
	s_barrier
	v_mfma_f32_16x16x32_bf16 v[128:131], v[132:135], v[204:207], v[128:131]
	v_mfma_f32_16x16x32_bf16 v[124:127], v[140:143], v[204:207], v[124:127]
	v_mfma_f32_16x16x32_bf16 v[112:115], v[132:135], v[212:215], v[112:115]
	v_mfma_f32_16x16x32_bf16 v[108:111], v[140:143], v[212:215], v[108:111]
	v_mfma_f32_16x16x32_bf16 v[94:97], v[132:135], v[220:223], v[94:97]
	v_mfma_f32_16x16x32_bf16 v[90:93], v[140:143], v[220:223], v[90:93]
	v_mfma_f32_16x16x32_bf16 v[78:81], v[132:135], v[238:241], v[78:81]
	v_mfma_f32_16x16x32_bf16 v[74:77], v[140:143], v[238:241], v[74:77]
	v_mfma_f32_16x16x32_bf16 v[128:131], v[136:139], v[208:211], v[128:131]
	v_mfma_f32_16x16x32_bf16 v[124:127], v[144:147], v[208:211], v[124:127]
	v_mfma_f32_16x16x32_bf16 v[112:115], v[136:139], v[216:219], v[112:115]
	v_mfma_f32_16x16x32_bf16 v[108:111], v[144:147], v[216:219], v[108:111]
	v_mfma_f32_16x16x32_bf16 v[94:97], v[136:139], v[224:227], v[94:97]
	v_mfma_f32_16x16x32_bf16 v[90:93], v[144:147], v[224:227], v[90:93]
	v_mfma_f32_16x16x32_bf16 v[78:81], v[136:139], v[242:245], v[78:81]
	v_mfma_f32_16x16x32_bf16 v[74:77], v[144:147], v[242:245], v[74:77]
	s_setprio 0
	s_setprio 1
	v_mfma_f32_16x16x32_bf16 v[120:123], v[156:159], v[204:207], v[120:123]
	v_mfma_f32_16x16x32_bf16 v[116:119], v[192:195], v[204:207], v[116:119]
	v_mfma_f32_16x16x32_bf16 v[104:107], v[156:159], v[212:215], v[104:107]
	v_mfma_f32_16x16x32_bf16 v[100:103], v[192:195], v[212:215], v[100:103]
	v_mfma_f32_16x16x32_bf16 v[86:89], v[156:159], v[220:223], v[86:89]
	v_mfma_f32_16x16x32_bf16 v[82:85], v[192:195], v[220:223], v[82:85]
	v_mfma_f32_16x16x32_bf16 v[70:73], v[156:159], v[238:241], v[70:73]
	v_mfma_f32_16x16x32_bf16 v[66:69], v[192:195], v[238:241], v[66:69]
	v_mfma_f32_16x16x32_bf16 v[120:123], v[162:165], v[208:211], v[120:123]
	v_mfma_f32_16x16x32_bf16 v[116:119], v[200:203], v[208:211], v[116:119]
	v_mfma_f32_16x16x32_bf16 v[104:107], v[162:165], v[216:219], v[104:107]
	v_mfma_f32_16x16x32_bf16 v[100:103], v[200:203], v[216:219], v[100:103]
	v_mfma_f32_16x16x32_bf16 v[86:89], v[162:165], v[224:227], v[86:89]
	v_mfma_f32_16x16x32_bf16 v[82:85], v[200:203], v[224:227], v[82:85]
	v_mfma_f32_16x16x32_bf16 v[70:73], v[162:165], v[242:245], v[70:73]
	v_mfma_f32_16x16x32_bf16 v[66:69], v[200:203], v[242:245], v[66:69]
	s_setprio 0
	s_barrier
	s_add_i32 s4, s6, s70
	v_lshl_add_u64 v[166:167], s[56:57], 0, v[148:149]
	s_mov_b32 m0, s4
	ds_read_b128 v[204:207], v191 offset:16384
	ds_read_b128 v[208:211], v191 offset:17408
	ds_read_b128 v[212:215], v191 offset:18432
	ds_read_b128 v[216:219], v191 offset:19456
	ds_read_b128 v[220:223], v191 offset:20480
	ds_read_b128 v[224:227], v191 offset:21504
	ds_read_b128 v[238:241], v191 offset:22528
	ds_read_b128 v[242:245], v191 offset:23552
	global_load_lds_dwordx4 v[166:167], off
	s_add_i32 m0, s4, 0x2000
	s_add_u32 s4, s56, 0x40000
	v_lshl_add_u64 v[170:171], s[56:57], 0, v[152:153]
	s_addc_u32 s5, s57, 0
	s_add_i32 s6, s7, s70
	global_load_lds_dwordx4 v[170:171], off
	v_lshl_add_u64 v[176:177], s[4:5], 0, v[148:149]
	s_mov_b32 m0, s6
	v_lshl_add_u64 v[180:181], s[68:69], 0, v[150:151]
	global_load_lds_dwordx4 v[176:177], off
	v_lshl_add_u64 v[176:177], s[4:5], 0, v[152:153]
	s_add_i32 m0, s6, 0x2000
	s_nop 0
	global_load_lds_dwordx4 v[176:177], off
	v_lshl_add_u64 v[176:177], s[68:69], 0, v[98:99]
	s_mov_b32 m0, s44
	s_nop 0
	global_load_lds_dwordx4 v[176:177], off
	s_add_i32 m0, s44, 0x2000
	s_nop 0
	global_load_lds_dwordx4 v[180:181], off
	s_waitcnt vmcnt(8)
	s_waitcnt lgkmcnt(0)
	s_setprio 1
	s_barrier
	v_mfma_f32_16x16x32_bf16 v[62:65], v[132:135], v[204:207], v[62:65]
	v_mfma_f32_16x16x32_bf16 v[58:61], v[140:143], v[204:207], v[58:61]
	v_mfma_f32_16x16x32_bf16 v[46:49], v[132:135], v[212:215], v[46:49]
	v_mfma_f32_16x16x32_bf16 v[42:45], v[140:143], v[212:215], v[42:45]
	v_mfma_f32_16x16x32_bf16 v[30:33], v[132:135], v[220:223], v[30:33]
	v_mfma_f32_16x16x32_bf16 v[26:29], v[140:143], v[220:223], v[26:29]
	v_mfma_f32_16x16x32_bf16 v[14:17], v[132:135], v[238:241], v[14:17]
	v_mfma_f32_16x16x32_bf16 v[10:13], v[140:143], v[238:241], v[10:13]
	v_mfma_f32_16x16x32_bf16 v[62:65], v[136:139], v[208:211], v[62:65]
	v_mfma_f32_16x16x32_bf16 v[58:61], v[144:147], v[208:211], v[58:61]
	v_mfma_f32_16x16x32_bf16 v[46:49], v[136:139], v[216:219], v[46:49]
	v_mfma_f32_16x16x32_bf16 v[42:45], v[144:147], v[216:219], v[42:45]
	v_mfma_f32_16x16x32_bf16 v[30:33], v[136:139], v[224:227], v[30:33]
	v_mfma_f32_16x16x32_bf16 v[26:29], v[144:147], v[224:227], v[26:29]
	v_mfma_f32_16x16x32_bf16 v[14:17], v[136:139], v[242:245], v[14:17]
	v_mfma_f32_16x16x32_bf16 v[10:13], v[144:147], v[242:245], v[10:13]
	s_setprio 0
	s_setprio 1
	v_mfma_f32_16x16x32_bf16 v[54:57], v[156:159], v[204:207], v[54:57]
	v_mfma_f32_16x16x32_bf16 v[50:53], v[192:195], v[204:207], v[50:53]
	v_mfma_f32_16x16x32_bf16 v[38:41], v[156:159], v[212:215], v[38:41]
	v_mfma_f32_16x16x32_bf16 v[34:37], v[192:195], v[212:215], v[34:37]
	v_mfma_f32_16x16x32_bf16 v[22:25], v[156:159], v[220:223], v[22:25]
	v_mfma_f32_16x16x32_bf16 v[18:21], v[192:195], v[220:223], v[18:21]
	v_mfma_f32_16x16x32_bf16 v[6:9], v[156:159], v[238:241], v[6:9]
	v_mfma_f32_16x16x32_bf16 v[2:5], v[192:195], v[238:241], v[2:5]
	v_mfma_f32_16x16x32_bf16 v[54:57], v[162:165], v[208:211], v[54:57]
	v_mfma_f32_16x16x32_bf16 v[50:53], v[200:203], v[208:211], v[50:53]
	v_mfma_f32_16x16x32_bf16 v[38:41], v[162:165], v[216:219], v[38:41]
	v_mfma_f32_16x16x32_bf16 v[34:37], v[200:203], v[216:219], v[34:37]
	v_mfma_f32_16x16x32_bf16 v[22:25], v[162:165], v[224:227], v[22:25]
	v_mfma_f32_16x16x32_bf16 v[18:21], v[200:203], v[224:227], v[18:21]
	v_mfma_f32_16x16x32_bf16 v[6:9], v[162:165], v[242:245], v[6:9]
	v_mfma_f32_16x16x32_bf16 v[2:5], v[200:203], v[242:245], v[2:5]
	s_setprio 0
	s_barrier
	s_add_i32 s6, 0, 0x18000
	s_add_i32 s7, 0, 0x1c000
	v_add_u32_e32 v144, s6, v189
	v_add_u32_e32 v160, s7, v189
	ds_read_b128 v[132:135], v144
	ds_read_b128 v[136:139], v144 offset:1024
	ds_read_b128 v[140:143], v144 offset:2048
	ds_read_b128 v[144:147], v144 offset:3072
	ds_read_b128 v[156:159], v160
	ds_read_b128 v[162:165], v160 offset:1024
	ds_read_b128 v[192:195], v160 offset:2048
	ds_read_b128 v[200:203], v160 offset:3072
	s_add_u32 s4, s68, 0x40000
	s_addc_u32 s5, s69, 0
	v_lshl_add_u64 v[246:247], s[4:5], 0, v[98:99]
	s_add_i32 m0, s44, 0x4000
	ds_read_b128 v[204:207], v191 offset:32768
	ds_read_b128 v[208:211], v191 offset:33792
	ds_read_b128 v[212:215], v191 offset:34816
	ds_read_b128 v[216:219], v191 offset:35840
	ds_read_b128 v[220:223], v191 offset:36864
	ds_read_b128 v[224:227], v191 offset:37888
	ds_read_b128 v[238:241], v191 offset:38912
	ds_read_b128 v[242:245], v191 offset:39936
	global_load_lds_dwordx4 v[246:247], off
	v_lshl_add_u64 v[246:247], s[4:5], 0, v[150:151]
	s_add_i32 m0, s44, 0x6000
	s_nop 0
	global_load_lds_dwordx4 v[246:247], off
	s_waitcnt vmcnt(8)
	s_waitcnt lgkmcnt(0)
	s_setprio 1
	s_barrier
	v_mfma_f32_16x16x32_bf16 v[128:131], v[132:135], v[204:207], v[128:131]
	v_mfma_f32_16x16x32_bf16 v[124:127], v[140:143], v[204:207], v[124:127]
	v_mfma_f32_16x16x32_bf16 v[112:115], v[132:135], v[212:215], v[112:115]
	v_mfma_f32_16x16x32_bf16 v[108:111], v[140:143], v[212:215], v[108:111]
	v_mfma_f32_16x16x32_bf16 v[94:97], v[132:135], v[220:223], v[94:97]
	v_mfma_f32_16x16x32_bf16 v[90:93], v[140:143], v[220:223], v[90:93]
	v_mfma_f32_16x16x32_bf16 v[78:81], v[132:135], v[238:241], v[78:81]
	v_mfma_f32_16x16x32_bf16 v[74:77], v[140:143], v[238:241], v[74:77]
	v_mfma_f32_16x16x32_bf16 v[128:131], v[136:139], v[208:211], v[128:131]
	v_mfma_f32_16x16x32_bf16 v[124:127], v[144:147], v[208:211], v[124:127]
	v_mfma_f32_16x16x32_bf16 v[112:115], v[136:139], v[216:219], v[112:115]
	v_mfma_f32_16x16x32_bf16 v[108:111], v[144:147], v[216:219], v[108:111]
	v_mfma_f32_16x16x32_bf16 v[94:97], v[136:139], v[224:227], v[94:97]
	v_mfma_f32_16x16x32_bf16 v[90:93], v[144:147], v[224:227], v[90:93]
	v_mfma_f32_16x16x32_bf16 v[78:81], v[136:139], v[242:245], v[78:81]
	v_mfma_f32_16x16x32_bf16 v[74:77], v[144:147], v[242:245], v[74:77]
	s_setprio 0
	s_setprio 1
	v_mfma_f32_16x16x32_bf16 v[120:123], v[156:159], v[204:207], v[120:123]
	v_mfma_f32_16x16x32_bf16 v[116:119], v[192:195], v[204:207], v[116:119]
	v_mfma_f32_16x16x32_bf16 v[104:107], v[156:159], v[212:215], v[104:107]
	v_mfma_f32_16x16x32_bf16 v[100:103], v[192:195], v[212:215], v[100:103]
	v_mfma_f32_16x16x32_bf16 v[86:89], v[156:159], v[220:223], v[86:89]
	v_mfma_f32_16x16x32_bf16 v[82:85], v[192:195], v[220:223], v[82:85]
	v_mfma_f32_16x16x32_bf16 v[70:73], v[156:159], v[238:241], v[70:73]
	v_mfma_f32_16x16x32_bf16 v[66:69], v[192:195], v[238:241], v[66:69]
	v_mfma_f32_16x16x32_bf16 v[120:123], v[162:165], v[208:211], v[120:123]
	v_mfma_f32_16x16x32_bf16 v[116:119], v[200:203], v[208:211], v[116:119]
	v_mfma_f32_16x16x32_bf16 v[104:107], v[162:165], v[216:219], v[104:107]
	v_mfma_f32_16x16x32_bf16 v[100:103], v[200:203], v[216:219], v[100:103]
	v_mfma_f32_16x16x32_bf16 v[86:89], v[162:165], v[224:227], v[86:89]
	v_mfma_f32_16x16x32_bf16 v[82:85], v[200:203], v[224:227], v[82:85]
	v_mfma_f32_16x16x32_bf16 v[70:73], v[162:165], v[242:245], v[70:73]
	v_mfma_f32_16x16x32_bf16 v[66:69], v[200:203], v[242:245], v[66:69]
	s_setprio 0
	s_barrier
	s_add_i32 s4, s6, s70
	v_lshl_add_u64 v[166:167], v[166:167], 0, s[42:43]
	s_mov_b32 m0, s4
	ds_read_b128 v[204:207], v191 offset:49152
	ds_read_b128 v[208:211], v191 offset:50176
	ds_read_b128 v[212:215], v191 offset:51200
	ds_read_b128 v[216:219], v191 offset:52224
	ds_read_b128 v[220:223], v191 offset:53248
	ds_read_b128 v[224:227], v191 offset:54272
	ds_read_b128 v[238:241], v191 offset:55296
	ds_read_b128 v[242:245], v191 offset:56320
	global_load_lds_dwordx4 v[166:167], off
	s_add_i32 m0, s4, 0x2000
	s_add_u32 s4, s56, 0x40080
	v_lshl_add_u64 v[166:167], v[170:171], 0, s[42:43]
	s_addc_u32 s5, s57, 0
	s_add_i32 s6, s7, s70
	global_load_lds_dwordx4 v[166:167], off
	v_lshl_add_u64 v[166:167], s[4:5], 0, v[148:149]
	s_mov_b32 m0, s6
	s_nop 0
	global_load_lds_dwordx4 v[166:167], off
	v_lshl_add_u64 v[166:167], s[4:5], 0, v[152:153]
	s_add_i32 m0, s6, 0x2000
	s_nop 0
	global_load_lds_dwordx4 v[166:167], off
	v_lshl_add_u64 v[166:167], v[176:177], 0, s[42:43]
	s_add_i32 m0, s44, 0x8000
	s_nop 0
	global_load_lds_dwordx4 v[166:167], off
	v_lshl_add_u64 v[166:167], v[180:181], 0, s[42:43]
	s_add_i32 m0, s44, 0xa000
	s_nop 0
	global_load_lds_dwordx4 v[166:167], off
	s_waitcnt vmcnt(8)
	s_waitcnt lgkmcnt(0)
	s_setprio 1
	s_barrier
	v_mfma_f32_16x16x32_bf16 v[62:65], v[132:135], v[204:207], v[62:65]
	v_mfma_f32_16x16x32_bf16 v[58:61], v[140:143], v[204:207], v[58:61]
	v_mfma_f32_16x16x32_bf16 v[46:49], v[132:135], v[212:215], v[46:49]
	v_mfma_f32_16x16x32_bf16 v[42:45], v[140:143], v[212:215], v[42:45]
	v_mfma_f32_16x16x32_bf16 v[30:33], v[132:135], v[220:223], v[30:33]
	v_mfma_f32_16x16x32_bf16 v[26:29], v[140:143], v[220:223], v[26:29]
	v_mfma_f32_16x16x32_bf16 v[14:17], v[132:135], v[238:241], v[14:17]
	v_mfma_f32_16x16x32_bf16 v[10:13], v[140:143], v[238:241], v[10:13]
	v_mfma_f32_16x16x32_bf16 v[62:65], v[136:139], v[208:211], v[62:65]
	v_mfma_f32_16x16x32_bf16 v[58:61], v[144:147], v[208:211], v[58:61]
	v_mfma_f32_16x16x32_bf16 v[46:49], v[136:139], v[216:219], v[46:49]
	v_mfma_f32_16x16x32_bf16 v[42:45], v[144:147], v[216:219], v[42:45]
	v_mfma_f32_16x16x32_bf16 v[30:33], v[136:139], v[224:227], v[30:33]
	v_mfma_f32_16x16x32_bf16 v[26:29], v[144:147], v[224:227], v[26:29]
	v_mfma_f32_16x16x32_bf16 v[14:17], v[136:139], v[242:245], v[14:17]
	v_mfma_f32_16x16x32_bf16 v[10:13], v[144:147], v[242:245], v[10:13]
	s_setprio 0
	s_setprio 1
	v_mfma_f32_16x16x32_bf16 v[54:57], v[156:159], v[204:207], v[54:57]
	v_mfma_f32_16x16x32_bf16 v[50:53], v[192:195], v[204:207], v[50:53]
	v_mfma_f32_16x16x32_bf16 v[38:41], v[156:159], v[212:215], v[38:41]
	v_mfma_f32_16x16x32_bf16 v[34:37], v[192:195], v[212:215], v[34:37]
	v_mfma_f32_16x16x32_bf16 v[22:25], v[156:159], v[220:223], v[22:25]
	v_mfma_f32_16x16x32_bf16 v[18:21], v[192:195], v[220:223], v[18:21]
	v_mfma_f32_16x16x32_bf16 v[6:9], v[156:159], v[238:241], v[6:9]
	v_mfma_f32_16x16x32_bf16 v[2:5], v[192:195], v[238:241], v[2:5]
	v_mfma_f32_16x16x32_bf16 v[54:57], v[162:165], v[208:211], v[54:57]
	v_mfma_f32_16x16x32_bf16 v[50:53], v[200:203], v[208:211], v[50:53]
	v_mfma_f32_16x16x32_bf16 v[38:41], v[162:165], v[216:219], v[38:41]
	v_mfma_f32_16x16x32_bf16 v[34:37], v[200:203], v[216:219], v[34:37]
	v_mfma_f32_16x16x32_bf16 v[22:25], v[162:165], v[224:227], v[22:25]
	v_mfma_f32_16x16x32_bf16 v[18:21], v[200:203], v[224:227], v[18:21]
	v_mfma_f32_16x16x32_bf16 v[6:9], v[162:165], v[242:245], v[6:9]
	v_mfma_f32_16x16x32_bf16 v[2:5], v[200:203], v[242:245], v[2:5]
	s_setprio 0
	s_barrier
	s_add_i32 s92, s92, 2
	s_add_u32 s40, s40, 0x100
	s_addc_u32 s41, s41, 0
	s_add_u32 s90, s90, 0x100
	s_addc_u32 s91, s91, 0
	s_cmp_gt_u32 s92, 13
	s_cbranch_scc0 .LBB0_1011
	s_mov_b32 s100, 1
	s_and_b64 vcc, exec, s[0:1]
	s_cbranch_vccz .LBB0_1014
	s_barrier

.LBB0_1116:
	s_add_u32 s4, s74, 0xfff00080
	s_addc_u32 s5, s75, -1
	s_add_i32 s6, 0, 0x10000
	s_cmp_eq_u32 s95, 60
	s_cselect_b32 vcc_hi, s18, s5
	s_cselect_b32 vcc_lo, s21, s4
	s_cselect_b32 s79, s27, s94
	s_cselect_b32 s78, s69, s71
	s_add_i32 s7, 0, 0x14000
	v_add_u32_e32 v128, s6, v205
	v_add_u32_e32 v160, s7, v205
	ds_read_b128 v[112:115], v128
	ds_read_b128 v[116:119], v128 offset:1024
	ds_read_b128 v[124:127], v128 offset:2048
	ds_read_b128 v[128:131], v128 offset:3072
	ds_read_b128 v[148:151], v160
	ds_read_b128 v[152:155], v160 offset:1024
	ds_read_b128 v[156:159], v160 offset:2048
	ds_read_b128 v[160:163], v160 offset:3072
	s_add_i32 s44, s91, 0
	v_lshl_add_u64 v[194:195], s[74:75], 0, v[98:99]
	s_add_i32 m0, s44, 0xc000
	ds_read_b128 v[164:167], v207
	ds_read_b128 v[168:171], v207 offset:1024
	ds_read_b128 v[178:181], v207 offset:2048
	ds_read_b128 v[182:185], v207 offset:3072
	ds_read_b128 v[186:189], v207 offset:4096
	ds_read_b128 v[190:193], v207 offset:5120
	ds_read_b128 v[200:203], v207 offset:6144
	ds_read_b128 v[208:211], v207 offset:7168
	global_load_lds_dwordx4 v[194:195], off
	v_lshl_add_u64 v[194:195], s[74:75], 0, v[174:175]
	s_add_i32 m0, s44, 0xe000
	s_nop 0
	global_load_lds_dwordx4 v[194:195], off
	s_waitcnt vmcnt(8)
	s_waitcnt lgkmcnt(0)
	s_setprio 1
	s_barrier
	v_mfma_f32_16x16x32_bf16 v[144:147], v[112:115], v[164:167], v[144:147]
	v_mfma_f32_16x16x32_bf16 v[140:143], v[124:127], v[164:167], v[140:143]
	v_mfma_f32_16x16x32_bf16 v[120:123], v[112:115], v[178:181], v[120:123]
	v_mfma_f32_16x16x32_bf16 v[108:111], v[124:127], v[178:181], v[108:111]
	v_mfma_f32_16x16x32_bf16 v[94:97], v[112:115], v[186:189], v[94:97]
	v_mfma_f32_16x16x32_bf16 v[90:93], v[124:127], v[186:189], v[90:93]
	v_mfma_f32_16x16x32_bf16 v[78:81], v[112:115], v[200:203], v[78:81]
	v_mfma_f32_16x16x32_bf16 v[74:77], v[124:127], v[200:203], v[74:77]
	v_mfma_f32_16x16x32_bf16 v[144:147], v[116:119], v[168:171], v[144:147]
	v_mfma_f32_16x16x32_bf16 v[140:143], v[128:131], v[168:171], v[140:143]
	v_mfma_f32_16x16x32_bf16 v[120:123], v[116:119], v[182:185], v[120:123]
	v_mfma_f32_16x16x32_bf16 v[108:111], v[128:131], v[182:185], v[108:111]
	v_mfma_f32_16x16x32_bf16 v[94:97], v[116:119], v[190:193], v[94:97]
	v_mfma_f32_16x16x32_bf16 v[90:93], v[128:131], v[190:193], v[90:93]
	v_mfma_f32_16x16x32_bf16 v[78:81], v[116:119], v[208:211], v[78:81]
	v_mfma_f32_16x16x32_bf16 v[74:77], v[128:131], v[208:211], v[74:77]
	s_setprio 0
	s_setprio 1
	v_mfma_f32_16x16x32_bf16 v[136:139], v[148:151], v[164:167], v[136:139]
	v_mfma_f32_16x16x32_bf16 v[132:135], v[156:159], v[164:167], v[132:135]
	v_mfma_f32_16x16x32_bf16 v[104:107], v[148:151], v[178:181], v[104:107]
	v_mfma_f32_16x16x32_bf16 v[100:103], v[156:159], v[178:181], v[100:103]
	v_mfma_f32_16x16x32_bf16 v[86:89], v[148:151], v[186:189], v[86:89]
	v_mfma_f32_16x16x32_bf16 v[82:85], v[156:159], v[186:189], v[82:85]
	v_mfma_f32_16x16x32_bf16 v[70:73], v[148:151], v[200:203], v[70:73]
	v_mfma_f32_16x16x32_bf16 v[66:69], v[156:159], v[200:203], v[66:69]
	v_mfma_f32_16x16x32_bf16 v[136:139], v[152:155], v[168:171], v[136:139]
	v_mfma_f32_16x16x32_bf16 v[132:135], v[160:163], v[168:171], v[132:135]
	v_mfma_f32_16x16x32_bf16 v[104:107], v[152:155], v[182:185], v[104:107]
	v_mfma_f32_16x16x32_bf16 v[100:103], v[160:163], v[182:185], v[100:103]
	v_mfma_f32_16x16x32_bf16 v[86:89], v[152:155], v[190:193], v[86:89]
	v_mfma_f32_16x16x32_bf16 v[82:85], v[160:163], v[190:193], v[82:85]
	v_mfma_f32_16x16x32_bf16 v[70:73], v[152:155], v[208:211], v[70:73]
	v_mfma_f32_16x16x32_bf16 v[66:69], v[160:163], v[208:211], v[66:69]
	s_setprio 0
	s_barrier
	s_add_i32 s4, s6, s91
	v_lshl_add_u64 v[194:195], s[78:79], 0, v[172:173]
	s_mov_b32 m0, s4
	ds_read_b128 v[164:167], v207 offset:16384
	ds_read_b128 v[168:171], v207 offset:17408
	ds_read_b128 v[178:181], v207 offset:18432
	ds_read_b128 v[182:185], v207 offset:19456
	ds_read_b128 v[186:189], v207 offset:20480
	ds_read_b128 v[190:193], v207 offset:21504
	ds_read_b128 v[200:203], v207 offset:22528
	ds_read_b128 v[208:211], v207 offset:23552
	global_load_lds_dwordx4 v[194:195], off
	s_add_i32 m0, s4, 0x2000
	s_add_u32 s4, s78, 0x100000
	v_lshl_add_u64 v[212:213], s[78:79], 0, v[176:177]
	s_addc_u32 s5, s79, 0
	s_add_i32 s6, s7, s91
	global_load_lds_dwordx4 v[212:213], off
	v_lshl_add_u64 v[214:215], s[4:5], 0, v[172:173]
	s_mov_b32 m0, s6
	v_lshl_add_u64 v[216:217], vcc, 0, v[174:175]
	global_load_lds_dwordx4 v[214:215], off
	v_lshl_add_u64 v[214:215], s[4:5], 0, v[176:177]
	s_add_i32 m0, s6, 0x2000
	s_nop 0
	global_load_lds_dwordx4 v[214:215], off
	v_lshl_add_u64 v[214:215], vcc, 0, v[98:99]
	s_mov_b32 m0, s44
	s_nop 0
	global_load_lds_dwordx4 v[214:215], off
	s_add_i32 m0, s44, 0x2000
	s_nop 0
	global_load_lds_dwordx4 v[216:217], off
	s_waitcnt vmcnt(8)
	s_waitcnt lgkmcnt(0)
	s_setprio 1
	s_barrier
	v_mfma_f32_16x16x32_bf16 v[62:65], v[112:115], v[164:167], v[62:65]
	v_mfma_f32_16x16x32_bf16 v[58:61], v[124:127], v[164:167], v[58:61]
	v_mfma_f32_16x16x32_bf16 v[46:49], v[112:115], v[178:181], v[46:49]
	v_mfma_f32_16x16x32_bf16 v[42:45], v[124:127], v[178:181], v[42:45]
	v_mfma_f32_16x16x32_bf16 v[30:33], v[112:115], v[186:189], v[30:33]
	v_mfma_f32_16x16x32_bf16 v[26:29], v[124:127], v[186:189], v[26:29]
	v_mfma_f32_16x16x32_bf16 v[14:17], v[112:115], v[200:203], v[14:17]
	v_mfma_f32_16x16x32_bf16 v[10:13], v[124:127], v[200:203], v[10:13]
	v_mfma_f32_16x16x32_bf16 v[62:65], v[116:119], v[168:171], v[62:65]
	v_mfma_f32_16x16x32_bf16 v[58:61], v[128:131], v[168:171], v[58:61]
	v_mfma_f32_16x16x32_bf16 v[46:49], v[116:119], v[182:185], v[46:49]
	v_mfma_f32_16x16x32_bf16 v[42:45], v[128:131], v[182:185], v[42:45]
	v_mfma_f32_16x16x32_bf16 v[30:33], v[116:119], v[190:193], v[30:33]
	v_mfma_f32_16x16x32_bf16 v[26:29], v[128:131], v[190:193], v[26:29]
	v_mfma_f32_16x16x32_bf16 v[14:17], v[116:119], v[208:211], v[14:17]
	v_mfma_f32_16x16x32_bf16 v[10:13], v[128:131], v[208:211], v[10:13]
	s_setprio 0
	s_setprio 1
	v_mfma_f32_16x16x32_bf16 v[54:57], v[148:151], v[164:167], v[54:57]
	v_mfma_f32_16x16x32_bf16 v[50:53], v[156:159], v[164:167], v[50:53]
	v_mfma_f32_16x16x32_bf16 v[38:41], v[148:151], v[178:181], v[38:41]
	v_mfma_f32_16x16x32_bf16 v[34:37], v[156:159], v[178:181], v[34:37]
	v_mfma_f32_16x16x32_bf16 v[22:25], v[148:151], v[186:189], v[22:25]
	v_mfma_f32_16x16x32_bf16 v[18:21], v[156:159], v[186:189], v[18:21]
	v_mfma_f32_16x16x32_bf16 v[6:9], v[148:151], v[200:203], v[6:9]
	v_mfma_f32_16x16x32_bf16 v[2:5], v[156:159], v[200:203], v[2:5]
	v_mfma_f32_16x16x32_bf16 v[54:57], v[152:155], v[168:171], v[54:57]
	v_mfma_f32_16x16x32_bf16 v[50:53], v[160:163], v[168:171], v[50:53]
	v_mfma_f32_16x16x32_bf16 v[38:41], v[152:155], v[182:185], v[38:41]
	v_mfma_f32_16x16x32_bf16 v[34:37], v[160:163], v[182:185], v[34:37]
	v_mfma_f32_16x16x32_bf16 v[22:25], v[152:155], v[190:193], v[22:25]
	v_mfma_f32_16x16x32_bf16 v[18:21], v[160:163], v[190:193], v[18:21]
	v_mfma_f32_16x16x32_bf16 v[6:9], v[152:155], v[208:211], v[6:9]
	v_mfma_f32_16x16x32_bf16 v[2:5], v[160:163], v[208:211], v[2:5]
	s_setprio 0
	s_barrier
	s_add_i32 s6, 0, 0x18000
	s_add_i32 s7, 0, 0x1c000
	v_add_u32_e32 v128, s6, v205
	v_add_u32_e32 v160, s7, v205
	ds_read_b128 v[112:115], v128
	ds_read_b128 v[116:119], v128 offset:1024
	ds_read_b128 v[124:127], v128 offset:2048
	ds_read_b128 v[128:131], v128 offset:3072
	ds_read_b128 v[148:151], v160
	ds_read_b128 v[152:155], v160 offset:1024
	ds_read_b128 v[156:159], v160 offset:2048
	ds_read_b128 v[160:163], v160 offset:3072
	s_add_u32 s4, vcc_lo, 0x100000
	s_addc_u32 s5, vcc_hi, 0
	v_lshl_add_u64 v[218:219], s[4:5], 0, v[98:99]
	s_add_i32 m0, s44, 0x4000
	ds_read_b128 v[164:167], v207 offset:32768
	ds_read_b128 v[168:171], v207 offset:33792
	ds_read_b128 v[178:181], v207 offset:34816
	ds_read_b128 v[182:185], v207 offset:35840
	ds_read_b128 v[186:189], v207 offset:36864
	ds_read_b128 v[190:193], v207 offset:37888
	ds_read_b128 v[200:203], v207 offset:38912
	ds_read_b128 v[208:211], v207 offset:39936
	global_load_lds_dwordx4 v[218:219], off
	v_lshl_add_u64 v[218:219], s[4:5], 0, v[174:175]
	s_add_i32 m0, s44, 0x6000
	s_nop 0
	global_load_lds_dwordx4 v[218:219], off
	s_waitcnt vmcnt(8)
	s_waitcnt lgkmcnt(0)
	s_setprio 1
	s_barrier
	v_mfma_f32_16x16x32_bf16 v[144:147], v[112:115], v[164:167], v[144:147]
	v_mfma_f32_16x16x32_bf16 v[140:143], v[124:127], v[164:167], v[140:143]
	v_mfma_f32_16x16x32_bf16 v[120:123], v[112:115], v[178:181], v[120:123]
	v_mfma_f32_16x16x32_bf16 v[108:111], v[124:127], v[178:181], v[108:111]
	v_mfma_f32_16x16x32_bf16 v[94:97], v[112:115], v[186:189], v[94:97]
	v_mfma_f32_16x16x32_bf16 v[90:93], v[124:127], v[186:189], v[90:93]
	v_mfma_f32_16x16x32_bf16 v[78:81], v[112:115], v[200:203], v[78:81]
	v_mfma_f32_16x16x32_bf16 v[74:77], v[124:127], v[200:203], v[74:77]
	v_mfma_f32_16x16x32_bf16 v[144:147], v[116:119], v[168:171], v[144:147]
	v_mfma_f32_16x16x32_bf16 v[140:143], v[128:131], v[168:171], v[140:143]
	v_mfma_f32_16x16x32_bf16 v[120:123], v[116:119], v[182:185], v[120:123]
	v_mfma_f32_16x16x32_bf16 v[108:111], v[128:131], v[182:185], v[108:111]
	v_mfma_f32_16x16x32_bf16 v[94:97], v[116:119], v[190:193], v[94:97]
	v_mfma_f32_16x16x32_bf16 v[90:93], v[128:131], v[190:193], v[90:93]
	v_mfma_f32_16x16x32_bf16 v[78:81], v[116:119], v[208:211], v[78:81]
	v_mfma_f32_16x16x32_bf16 v[74:77], v[128:131], v[208:211], v[74:77]
	s_setprio 0
	s_setprio 1
	v_mfma_f32_16x16x32_bf16 v[136:139], v[148:151], v[164:167], v[136:139]
	v_mfma_f32_16x16x32_bf16 v[132:135], v[156:159], v[164:167], v[132:135]
	v_mfma_f32_16x16x32_bf16 v[104:107], v[148:151], v[178:181], v[104:107]
	v_mfma_f32_16x16x32_bf16 v[100:103], v[156:159], v[178:181], v[100:103]
	v_mfma_f32_16x16x32_bf16 v[86:89], v[148:151], v[186:189], v[86:89]
	v_mfma_f32_16x16x32_bf16 v[82:85], v[156:159], v[186:189], v[82:85]
	v_mfma_f32_16x16x32_bf16 v[70:73], v[148:151], v[200:203], v[70:73]
	v_mfma_f32_16x16x32_bf16 v[66:69], v[156:159], v[200:203], v[66:69]
	v_mfma_f32_16x16x32_bf16 v[136:139], v[152:155], v[168:171], v[136:139]
	v_mfma_f32_16x16x32_bf16 v[132:135], v[160:163], v[168:171], v[132:135]
	v_mfma_f32_16x16x32_bf16 v[104:107], v[152:155], v[182:185], v[104:107]
	v_mfma_f32_16x16x32_bf16 v[100:103], v[160:163], v[182:185], v[100:103]
	v_mfma_f32_16x16x32_bf16 v[86:89], v[152:155], v[190:193], v[86:89]
	v_mfma_f32_16x16x32_bf16 v[82:85], v[160:163], v[190:193], v[82:85]
	v_mfma_f32_16x16x32_bf16 v[70:73], v[152:155], v[208:211], v[70:73]
	v_mfma_f32_16x16x32_bf16 v[66:69], v[160:163], v[208:211], v[66:69]
	s_setprio 0
	s_barrier
	s_add_i32 s4, s6, s91
	v_lshl_add_u64 v[194:195], v[194:195], 0, s[42:43]
	s_mov_b32 m0, s4
	ds_read_b128 v[164:167], v207 offset:49152
	ds_read_b128 v[168:171], v207 offset:50176
	ds_read_b128 v[178:181], v207 offset:51200
	ds_read_b128 v[182:185], v207 offset:52224
	ds_read_b128 v[186:189], v207 offset:53248
	ds_read_b128 v[190:193], v207 offset:54272
	ds_read_b128 v[200:203], v207 offset:55296
	ds_read_b128 v[208:211], v207 offset:56320
	global_load_lds_dwordx4 v[194:195], off
	s_add_i32 m0, s4, 0x2000
	s_add_u32 s4, s78, 0x100080
	v_lshl_add_u64 v[194:195], v[212:213], 0, s[42:43]
	s_addc_u32 s5, s79, 0
	s_add_i32 s6, s7, s91
	global_load_lds_dwordx4 v[194:195], off
	v_lshl_add_u64 v[194:195], s[4:5], 0, v[172:173]
	s_mov_b32 m0, s6
	s_nop 0
	global_load_lds_dwordx4 v[194:195], off
	v_lshl_add_u64 v[194:195], s[4:5], 0, v[176:177]
	s_add_i32 m0, s6, 0x2000
	s_nop 0
	global_load_lds_dwordx4 v[194:195], off
	v_lshl_add_u64 v[194:195], v[214:215], 0, s[42:43]
	s_add_i32 m0, s44, 0x8000
	s_nop 0
	global_load_lds_dwordx4 v[194:195], off
	v_lshl_add_u64 v[194:195], v[216:217], 0, s[42:43]
	s_add_i32 m0, s44, 0xa000
	s_nop 0
	global_load_lds_dwordx4 v[194:195], off
	s_waitcnt vmcnt(8)
	s_waitcnt lgkmcnt(0)
	s_setprio 1
	s_barrier
	v_mfma_f32_16x16x32_bf16 v[62:65], v[112:115], v[164:167], v[62:65]
	v_mfma_f32_16x16x32_bf16 v[58:61], v[124:127], v[164:167], v[58:61]
	v_mfma_f32_16x16x32_bf16 v[46:49], v[112:115], v[178:181], v[46:49]
	v_mfma_f32_16x16x32_bf16 v[42:45], v[124:127], v[178:181], v[42:45]
	v_mfma_f32_16x16x32_bf16 v[30:33], v[112:115], v[186:189], v[30:33]
	v_mfma_f32_16x16x32_bf16 v[26:29], v[124:127], v[186:189], v[26:29]
	v_mfma_f32_16x16x32_bf16 v[14:17], v[112:115], v[200:203], v[14:17]
	v_mfma_f32_16x16x32_bf16 v[10:13], v[124:127], v[200:203], v[10:13]
	v_mfma_f32_16x16x32_bf16 v[62:65], v[116:119], v[168:171], v[62:65]
	v_mfma_f32_16x16x32_bf16 v[58:61], v[128:131], v[168:171], v[58:61]
	v_mfma_f32_16x16x32_bf16 v[46:49], v[116:119], v[182:185], v[46:49]
	v_mfma_f32_16x16x32_bf16 v[42:45], v[128:131], v[182:185], v[42:45]
	v_mfma_f32_16x16x32_bf16 v[30:33], v[116:119], v[190:193], v[30:33]
	v_mfma_f32_16x16x32_bf16 v[26:29], v[128:131], v[190:193], v[26:29]
	v_mfma_f32_16x16x32_bf16 v[14:17], v[116:119], v[208:211], v[14:17]
	v_mfma_f32_16x16x32_bf16 v[10:13], v[128:131], v[208:211], v[10:13]
	s_setprio 0
	s_setprio 1
	v_mfma_f32_16x16x32_bf16 v[54:57], v[148:151], v[164:167], v[54:57]
	v_mfma_f32_16x16x32_bf16 v[50:53], v[156:159], v[164:167], v[50:53]
	v_mfma_f32_16x16x32_bf16 v[38:41], v[148:151], v[178:181], v[38:41]
	v_mfma_f32_16x16x32_bf16 v[34:37], v[156:159], v[178:181], v[34:37]
	v_mfma_f32_16x16x32_bf16 v[22:25], v[148:151], v[186:189], v[22:25]
	v_mfma_f32_16x16x32_bf16 v[18:21], v[156:159], v[186:189], v[18:21]
	v_mfma_f32_16x16x32_bf16 v[6:9], v[148:151], v[200:203], v[6:9]
	v_mfma_f32_16x16x32_bf16 v[2:5], v[156:159], v[200:203], v[2:5]
	v_mfma_f32_16x16x32_bf16 v[54:57], v[152:155], v[168:171], v[54:57]
	v_mfma_f32_16x16x32_bf16 v[50:53], v[160:163], v[168:171], v[50:53]
	v_mfma_f32_16x16x32_bf16 v[38:41], v[152:155], v[182:185], v[38:41]
	v_mfma_f32_16x16x32_bf16 v[34:37], v[160:163], v[182:185], v[34:37]
	v_mfma_f32_16x16x32_bf16 v[22:25], v[152:155], v[190:193], v[22:25]
	v_mfma_f32_16x16x32_bf16 v[18:21], v[160:163], v[190:193], v[18:21]
	v_mfma_f32_16x16x32_bf16 v[6:9], v[152:155], v[208:211], v[6:9]
	v_mfma_f32_16x16x32_bf16 v[2:5], v[160:163], v[208:211], v[2:5]
	s_setprio 0
	s_barrier
	s_add_i32 s95, s95, 2
	s_add_u32 s74, s74, 0x100
	s_addc_u32 s75, s75, 0
	s_add_u32 s71, s71, 0x100
	s_addc_u32 s94, s94, 0
	s_cmp_gt_u32 s95, 61
	s_cbranch_scc0 .LBB0_1116
	s_mov_b32 s100, 1
	s_and_b64 vcc, exec, s[10:11]
	s_cbranch_vccz .LBB0_1119
	s_barrier

.LBB0_1172:
	s_add_u32 s4, s70, 0xfff00080
	s_addc_u32 s5, s71, -1
	s_add_i32 s6, 0, 0x10000
	s_cmp_eq_u32 s95, 60
	s_cselect_b32 s79, s18, s5
	s_cselect_b32 s78, s27, s4
	s_cselect_b32 s75, s15, s94
	s_cselect_b32 s74, s57, s69
	s_add_i32 s7, 0, 0x14000
	v_add_u32_e32 v104, s6, v239
	v_add_u32_e32 v128, s7, v239
	ds_read_b128 v[90:93], v104
	ds_read_b128 v[94:97], v104 offset:1024
	ds_read_b128 v[100:103], v104 offset:2048
	ds_read_b128 v[104:107], v104 offset:3072
	ds_read_b128 v[108:111], v128
	ds_read_b128 v[112:115], v128 offset:1024
	ds_read_b128 v[120:123], v128 offset:2048
	ds_read_b128 v[128:131], v128 offset:3072
	s_add_i32 s44, s91, 0
	v_lshl_add_u64 v[200:201], s[70:71], 0, v[98:99]
	s_add_i32 m0, s44, 0xc000
	ds_read_b128 v[164:167], v241
	ds_read_b128 v[168:171], v241 offset:1024
	ds_read_b128 v[172:175], v241 offset:2048
	ds_read_b128 v[176:179], v241 offset:3072
	ds_read_b128 v[180:183], v241 offset:4096
	ds_read_b128 v[184:187], v241 offset:5120
	ds_read_b128 v[188:191], v241 offset:6144
	ds_read_b128 v[192:195], v241 offset:7168
	global_load_lds_dwordx4 v[200:201], off
	v_lshl_add_u64 v[200:201], s[70:71], 0, v[206:207]
	s_add_i32 m0, s44, 0xe000
	s_nop 0
	global_load_lds_dwordx4 v[200:201], off
	s_waitcnt vmcnt(8)
	s_waitcnt lgkmcnt(0)
	s_setprio 1
	s_barrier
	v_mfma_f32_16x16x32_bf16 v[160:163], v[90:93], v[164:167], v[160:163]
	v_mfma_f32_16x16x32_bf16 v[156:159], v[100:103], v[164:167], v[156:159]
	v_mfma_f32_16x16x32_bf16 v[144:147], v[90:93], v[172:175], v[144:147]
	v_mfma_f32_16x16x32_bf16 v[140:143], v[100:103], v[172:175], v[140:143]
	v_mfma_f32_16x16x32_bf16 v[124:127], v[90:93], v[180:183], v[124:127]
	v_mfma_f32_16x16x32_bf16 v[116:119], v[100:103], v[180:183], v[116:119]
	v_mfma_f32_16x16x32_bf16 v[78:81], v[90:93], v[188:191], v[78:81]
	v_mfma_f32_16x16x32_bf16 v[74:77], v[100:103], v[188:191], v[74:77]
	v_mfma_f32_16x16x32_bf16 v[160:163], v[94:97], v[168:171], v[160:163]
	v_mfma_f32_16x16x32_bf16 v[156:159], v[104:107], v[168:171], v[156:159]
	v_mfma_f32_16x16x32_bf16 v[144:147], v[94:97], v[176:179], v[144:147]
	v_mfma_f32_16x16x32_bf16 v[140:143], v[104:107], v[176:179], v[140:143]
	v_mfma_f32_16x16x32_bf16 v[124:127], v[94:97], v[184:187], v[124:127]
	v_mfma_f32_16x16x32_bf16 v[116:119], v[104:107], v[184:187], v[116:119]
	v_mfma_f32_16x16x32_bf16 v[78:81], v[94:97], v[192:195], v[78:81]
	v_mfma_f32_16x16x32_bf16 v[74:77], v[104:107], v[192:195], v[74:77]
	s_setprio 0
	s_setprio 1
	v_mfma_f32_16x16x32_bf16 v[152:155], v[108:111], v[164:167], v[152:155]
	v_mfma_f32_16x16x32_bf16 v[148:151], v[120:123], v[164:167], v[148:151]
	v_mfma_f32_16x16x32_bf16 v[136:139], v[108:111], v[172:175], v[136:139]
	v_mfma_f32_16x16x32_bf16 v[132:135], v[120:123], v[172:175], v[132:135]
	v_mfma_f32_16x16x32_bf16 v[86:89], v[108:111], v[180:183], v[86:89]
	v_mfma_f32_16x16x32_bf16 v[82:85], v[120:123], v[180:183], v[82:85]
	v_mfma_f32_16x16x32_bf16 v[70:73], v[108:111], v[188:191], v[70:73]
	v_mfma_f32_16x16x32_bf16 v[66:69], v[120:123], v[188:191], v[66:69]
	v_mfma_f32_16x16x32_bf16 v[152:155], v[112:115], v[168:171], v[152:155]
	v_mfma_f32_16x16x32_bf16 v[148:151], v[128:131], v[168:171], v[148:151]
	v_mfma_f32_16x16x32_bf16 v[136:139], v[112:115], v[176:179], v[136:139]
	v_mfma_f32_16x16x32_bf16 v[132:135], v[128:131], v[176:179], v[132:135]
	v_mfma_f32_16x16x32_bf16 v[86:89], v[112:115], v[184:187], v[86:89]
	v_mfma_f32_16x16x32_bf16 v[82:85], v[128:131], v[184:187], v[82:85]
	v_mfma_f32_16x16x32_bf16 v[70:73], v[112:115], v[192:195], v[70:73]
	v_mfma_f32_16x16x32_bf16 v[66:69], v[128:131], v[192:195], v[66:69]
	s_setprio 0
	s_barrier
	s_add_i32 s4, s6, s91
	v_lshl_add_u64 v[200:201], s[74:75], 0, v[204:205]
	s_mov_b32 m0, s4
	ds_read_b128 v[164:167], v241 offset:16384
	ds_read_b128 v[168:171], v241 offset:17408
	ds_read_b128 v[172:175], v241 offset:18432
	ds_read_b128 v[176:179], v241 offset:19456
	ds_read_b128 v[180:183], v241 offset:20480
	ds_read_b128 v[184:187], v241 offset:21504
	ds_read_b128 v[188:191], v241 offset:22528
	ds_read_b128 v[192:195], v241 offset:23552
	global_load_lds_dwordx4 v[200:201], off
	s_add_i32 m0, s4, 0x2000
	s_add_u32 s4, s74, 0x100000
	v_lshl_add_u64 v[202:203], s[74:75], 0, v[208:209]
	s_addc_u32 s5, s75, 0
	s_add_i32 s6, s7, s91
	global_load_lds_dwordx4 v[202:203], off
	v_lshl_add_u64 v[210:211], s[4:5], 0, v[204:205]
	s_mov_b32 m0, s6
	v_lshl_add_u64 v[212:213], s[78:79], 0, v[206:207]
	global_load_lds_dwordx4 v[210:211], off
	v_lshl_add_u64 v[210:211], s[4:5], 0, v[208:209]
	s_add_i32 m0, s6, 0x2000
	s_nop 0
	global_load_lds_dwordx4 v[210:211], off
	v_lshl_add_u64 v[210:211], s[78:79], 0, v[98:99]
	s_mov_b32 m0, s44
	s_nop 0
	global_load_lds_dwordx4 v[210:211], off
	s_add_i32 m0, s44, 0x2000
	s_nop 0
	global_load_lds_dwordx4 v[212:213], off
	s_waitcnt vmcnt(8)
	s_waitcnt lgkmcnt(0)
	s_setprio 1
	s_barrier
	v_mfma_f32_16x16x32_bf16 v[62:65], v[90:93], v[164:167], v[62:65]
	v_mfma_f32_16x16x32_bf16 v[58:61], v[100:103], v[164:167], v[58:61]
	v_mfma_f32_16x16x32_bf16 v[46:49], v[90:93], v[172:175], v[46:49]
	v_mfma_f32_16x16x32_bf16 v[42:45], v[100:103], v[172:175], v[42:45]
	v_mfma_f32_16x16x32_bf16 v[30:33], v[90:93], v[180:183], v[30:33]
	v_mfma_f32_16x16x32_bf16 v[26:29], v[100:103], v[180:183], v[26:29]
	v_mfma_f32_16x16x32_bf16 v[14:17], v[90:93], v[188:191], v[14:17]
	v_mfma_f32_16x16x32_bf16 v[10:13], v[100:103], v[188:191], v[10:13]
	v_mfma_f32_16x16x32_bf16 v[62:65], v[94:97], v[168:171], v[62:65]
	v_mfma_f32_16x16x32_bf16 v[58:61], v[104:107], v[168:171], v[58:61]
	v_mfma_f32_16x16x32_bf16 v[46:49], v[94:97], v[176:179], v[46:49]
	v_mfma_f32_16x16x32_bf16 v[42:45], v[104:107], v[176:179], v[42:45]
	v_mfma_f32_16x16x32_bf16 v[30:33], v[94:97], v[184:187], v[30:33]
	v_mfma_f32_16x16x32_bf16 v[26:29], v[104:107], v[184:187], v[26:29]
	v_mfma_f32_16x16x32_bf16 v[14:17], v[94:97], v[192:195], v[14:17]
	v_mfma_f32_16x16x32_bf16 v[10:13], v[104:107], v[192:195], v[10:13]
	s_setprio 0
	s_setprio 1
	v_mfma_f32_16x16x32_bf16 v[54:57], v[108:111], v[164:167], v[54:57]
	v_mfma_f32_16x16x32_bf16 v[50:53], v[120:123], v[164:167], v[50:53]
	v_mfma_f32_16x16x32_bf16 v[38:41], v[108:111], v[172:175], v[38:41]
	v_mfma_f32_16x16x32_bf16 v[34:37], v[120:123], v[172:175], v[34:37]
	v_mfma_f32_16x16x32_bf16 v[22:25], v[108:111], v[180:183], v[22:25]
	v_mfma_f32_16x16x32_bf16 v[18:21], v[120:123], v[180:183], v[18:21]
	v_mfma_f32_16x16x32_bf16 v[6:9], v[108:111], v[188:191], v[6:9]
	v_mfma_f32_16x16x32_bf16 v[2:5], v[120:123], v[188:191], v[2:5]
	v_mfma_f32_16x16x32_bf16 v[54:57], v[112:115], v[168:171], v[54:57]
	v_mfma_f32_16x16x32_bf16 v[50:53], v[128:131], v[168:171], v[50:53]
	v_mfma_f32_16x16x32_bf16 v[38:41], v[112:115], v[176:179], v[38:41]
	v_mfma_f32_16x16x32_bf16 v[34:37], v[128:131], v[176:179], v[34:37]
	v_mfma_f32_16x16x32_bf16 v[22:25], v[112:115], v[184:187], v[22:25]
	v_mfma_f32_16x16x32_bf16 v[18:21], v[128:131], v[184:187], v[18:21]
	v_mfma_f32_16x16x32_bf16 v[6:9], v[112:115], v[192:195], v[6:9]
	v_mfma_f32_16x16x32_bf16 v[2:5], v[128:131], v[192:195], v[2:5]
	s_setprio 0
	s_barrier
	s_add_i32 s6, 0, 0x18000
	s_add_i32 s7, 0, 0x1c000
	v_add_u32_e32 v104, s6, v239
	v_add_u32_e32 v128, s7, v239
	ds_read_b128 v[90:93], v104
	ds_read_b128 v[94:97], v104 offset:1024
	ds_read_b128 v[100:103], v104 offset:2048
	ds_read_b128 v[104:107], v104 offset:3072
	ds_read_b128 v[108:111], v128
	ds_read_b128 v[112:115], v128 offset:1024
	ds_read_b128 v[120:123], v128 offset:2048
	ds_read_b128 v[128:131], v128 offset:3072
	s_add_u32 s4, s78, 0x100000
	s_addc_u32 s5, s79, 0
	v_lshl_add_u64 v[214:215], s[4:5], 0, v[98:99]
	s_add_i32 m0, s44, 0x4000
	ds_read_b128 v[164:167], v241 offset:32768
	ds_read_b128 v[168:171], v241 offset:33792
	ds_read_b128 v[172:175], v241 offset:34816
	ds_read_b128 v[176:179], v241 offset:35840
	ds_read_b128 v[180:183], v241 offset:36864
	ds_read_b128 v[184:187], v241 offset:37888
	ds_read_b128 v[188:191], v241 offset:38912
	ds_read_b128 v[192:195], v241 offset:39936
	global_load_lds_dwordx4 v[214:215], off
	v_lshl_add_u64 v[214:215], s[4:5], 0, v[206:207]
	s_add_i32 m0, s44, 0x6000
	s_nop 0
	global_load_lds_dwordx4 v[214:215], off
	s_waitcnt vmcnt(8)
	s_waitcnt lgkmcnt(0)
	s_setprio 1
	s_barrier
	v_mfma_f32_16x16x32_bf16 v[160:163], v[90:93], v[164:167], v[160:163]
	v_mfma_f32_16x16x32_bf16 v[156:159], v[100:103], v[164:167], v[156:159]
	v_mfma_f32_16x16x32_bf16 v[144:147], v[90:93], v[172:175], v[144:147]
	v_mfma_f32_16x16x32_bf16 v[140:143], v[100:103], v[172:175], v[140:143]
	v_mfma_f32_16x16x32_bf16 v[124:127], v[90:93], v[180:183], v[124:127]
	v_mfma_f32_16x16x32_bf16 v[116:119], v[100:103], v[180:183], v[116:119]
	v_mfma_f32_16x16x32_bf16 v[78:81], v[90:93], v[188:191], v[78:81]
	v_mfma_f32_16x16x32_bf16 v[74:77], v[100:103], v[188:191], v[74:77]
	v_mfma_f32_16x16x32_bf16 v[160:163], v[94:97], v[168:171], v[160:163]
	v_mfma_f32_16x16x32_bf16 v[156:159], v[104:107], v[168:171], v[156:159]
	v_mfma_f32_16x16x32_bf16 v[144:147], v[94:97], v[176:179], v[144:147]
	v_mfma_f32_16x16x32_bf16 v[140:143], v[104:107], v[176:179], v[140:143]
	v_mfma_f32_16x16x32_bf16 v[124:127], v[94:97], v[184:187], v[124:127]
	v_mfma_f32_16x16x32_bf16 v[116:119], v[104:107], v[184:187], v[116:119]
	v_mfma_f32_16x16x32_bf16 v[78:81], v[94:97], v[192:195], v[78:81]
	v_mfma_f32_16x16x32_bf16 v[74:77], v[104:107], v[192:195], v[74:77]
	s_setprio 0
	s_setprio 1
	v_mfma_f32_16x16x32_bf16 v[152:155], v[108:111], v[164:167], v[152:155]
	v_mfma_f32_16x16x32_bf16 v[148:151], v[120:123], v[164:167], v[148:151]
	v_mfma_f32_16x16x32_bf16 v[136:139], v[108:111], v[172:175], v[136:139]
	v_mfma_f32_16x16x32_bf16 v[132:135], v[120:123], v[172:175], v[132:135]
	v_mfma_f32_16x16x32_bf16 v[86:89], v[108:111], v[180:183], v[86:89]
	v_mfma_f32_16x16x32_bf16 v[82:85], v[120:123], v[180:183], v[82:85]
	v_mfma_f32_16x16x32_bf16 v[70:73], v[108:111], v[188:191], v[70:73]
	v_mfma_f32_16x16x32_bf16 v[66:69], v[120:123], v[188:191], v[66:69]
	v_mfma_f32_16x16x32_bf16 v[152:155], v[112:115], v[168:171], v[152:155]
	v_mfma_f32_16x16x32_bf16 v[148:151], v[128:131], v[168:171], v[148:151]
	v_mfma_f32_16x16x32_bf16 v[136:139], v[112:115], v[176:179], v[136:139]
	v_mfma_f32_16x16x32_bf16 v[132:135], v[128:131], v[176:179], v[132:135]
	v_mfma_f32_16x16x32_bf16 v[86:89], v[112:115], v[184:187], v[86:89]
	v_mfma_f32_16x16x32_bf16 v[82:85], v[128:131], v[184:187], v[82:85]
	v_mfma_f32_16x16x32_bf16 v[70:73], v[112:115], v[192:195], v[70:73]
	v_mfma_f32_16x16x32_bf16 v[66:69], v[128:131], v[192:195], v[66:69]
	s_setprio 0
	s_barrier
	s_add_i32 s4, s6, s91
	v_lshl_add_u64 v[200:201], v[200:201], 0, s[42:43]
	s_mov_b32 m0, s4
	ds_read_b128 v[164:167], v241 offset:49152
	ds_read_b128 v[168:171], v241 offset:50176
	ds_read_b128 v[172:175], v241 offset:51200
	ds_read_b128 v[176:179], v241 offset:52224
	ds_read_b128 v[180:183], v241 offset:53248
	ds_read_b128 v[184:187], v241 offset:54272
	ds_read_b128 v[188:191], v241 offset:55296
	ds_read_b128 v[192:195], v241 offset:56320
	global_load_lds_dwordx4 v[200:201], off
	s_add_i32 m0, s4, 0x2000
	s_add_u32 s4, s74, 0x100080
	v_lshl_add_u64 v[200:201], v[202:203], 0, s[42:43]
	s_addc_u32 s5, s75, 0
	s_add_i32 s6, s7, s91
	global_load_lds_dwordx4 v[200:201], off
	v_lshl_add_u64 v[200:201], s[4:5], 0, v[204:205]
	s_mov_b32 m0, s6
	s_nop 0
	global_load_lds_dwordx4 v[200:201], off
	v_lshl_add_u64 v[200:201], s[4:5], 0, v[208:209]
	s_add_i32 m0, s6, 0x2000
	s_nop 0
	global_load_lds_dwordx4 v[200:201], off
	v_lshl_add_u64 v[200:201], v[210:211], 0, s[42:43]
	s_add_i32 m0, s44, 0x8000
	s_nop 0
	global_load_lds_dwordx4 v[200:201], off
	v_lshl_add_u64 v[200:201], v[212:213], 0, s[42:43]
	s_add_i32 m0, s44, 0xa000
	s_nop 0
	global_load_lds_dwordx4 v[200:201], off
	s_waitcnt vmcnt(8)
	s_waitcnt lgkmcnt(0)
	s_setprio 1
	s_barrier
	v_mfma_f32_16x16x32_bf16 v[62:65], v[90:93], v[164:167], v[62:65]
	v_mfma_f32_16x16x32_bf16 v[58:61], v[100:103], v[164:167], v[58:61]
	v_mfma_f32_16x16x32_bf16 v[46:49], v[90:93], v[172:175], v[46:49]
	v_mfma_f32_16x16x32_bf16 v[42:45], v[100:103], v[172:175], v[42:45]
	v_mfma_f32_16x16x32_bf16 v[30:33], v[90:93], v[180:183], v[30:33]
	v_mfma_f32_16x16x32_bf16 v[26:29], v[100:103], v[180:183], v[26:29]
	v_mfma_f32_16x16x32_bf16 v[14:17], v[90:93], v[188:191], v[14:17]
	v_mfma_f32_16x16x32_bf16 v[10:13], v[100:103], v[188:191], v[10:13]
	v_mfma_f32_16x16x32_bf16 v[62:65], v[94:97], v[168:171], v[62:65]
	v_mfma_f32_16x16x32_bf16 v[58:61], v[104:107], v[168:171], v[58:61]
	v_mfma_f32_16x16x32_bf16 v[46:49], v[94:97], v[176:179], v[46:49]
	v_mfma_f32_16x16x32_bf16 v[42:45], v[104:107], v[176:179], v[42:45]
	v_mfma_f32_16x16x32_bf16 v[30:33], v[94:97], v[184:187], v[30:33]
	v_mfma_f32_16x16x32_bf16 v[26:29], v[104:107], v[184:187], v[26:29]
	v_mfma_f32_16x16x32_bf16 v[14:17], v[94:97], v[192:195], v[14:17]
	v_mfma_f32_16x16x32_bf16 v[10:13], v[104:107], v[192:195], v[10:13]
	s_setprio 0
	s_setprio 1
	v_mfma_f32_16x16x32_bf16 v[54:57], v[108:111], v[164:167], v[54:57]
	v_mfma_f32_16x16x32_bf16 v[50:53], v[120:123], v[164:167], v[50:53]
	v_mfma_f32_16x16x32_bf16 v[38:41], v[108:111], v[172:175], v[38:41]
	v_mfma_f32_16x16x32_bf16 v[34:37], v[120:123], v[172:175], v[34:37]
	v_mfma_f32_16x16x32_bf16 v[22:25], v[108:111], v[180:183], v[22:25]
	v_mfma_f32_16x16x32_bf16 v[18:21], v[120:123], v[180:183], v[18:21]
	v_mfma_f32_16x16x32_bf16 v[6:9], v[108:111], v[188:191], v[6:9]
	v_mfma_f32_16x16x32_bf16 v[2:5], v[120:123], v[188:191], v[2:5]
	v_mfma_f32_16x16x32_bf16 v[54:57], v[112:115], v[168:171], v[54:57]
	v_mfma_f32_16x16x32_bf16 v[50:53], v[128:131], v[168:171], v[50:53]
	v_mfma_f32_16x16x32_bf16 v[38:41], v[112:115], v[176:179], v[38:41]
	v_mfma_f32_16x16x32_bf16 v[34:37], v[128:131], v[176:179], v[34:37]
	v_mfma_f32_16x16x32_bf16 v[22:25], v[112:115], v[184:187], v[22:25]
	v_mfma_f32_16x16x32_bf16 v[18:21], v[128:131], v[184:187], v[18:21]
	v_mfma_f32_16x16x32_bf16 v[6:9], v[112:115], v[192:195], v[6:9]
	v_mfma_f32_16x16x32_bf16 v[2:5], v[128:131], v[192:195], v[2:5]
	s_setprio 0
	s_barrier
	s_add_i32 s95, s95, 2
	s_add_u32 s70, s70, 0x100
	s_addc_u32 s71, s71, 0
	s_add_u32 s69, s69, 0x100
	s_addc_u32 s94, s94, 0
	s_cmp_gt_u32 s95, 61
	s_cbranch_scc0 .LBB0_1172
	s_mov_b32 s100, 1
	s_and_b64 vcc, exec, s[10:11]
	s_cbranch_vccz .LBB0_1175
	s_barrier
